# GEMM load segments: the vmcnt and lgkmcnt waits fused into one s_waitcnt before the segment barrier
# speedup vs baseline: 1.0024x; 1.0024x over previous
.LBB0_22:
	s_add_u32 s18, s6, 0xfff80080
	s_addc_u32 s19, s7, -1
	s_add_i32 s41, 0, 0x10000
	s_cmp_eq_u32 s40, 28
	s_cselect_b32 s21, s13, s19
	s_cselect_b32 s20, s36, s18
	s_cselect_b32 s19, s11, s39
	s_cselect_b32 s18, s37, s38
	s_add_i32 s44, 0, 0x14000
	v_add_u32_e32 v140, s41, v175
	v_add_u32_e32 v166, s44, v175
	ds_read_b128 v[128:131], v140
	ds_read_b128 v[132:135], v140 offset:1024
	ds_read_b128 v[136:139], v140 offset:2048
	ds_read_b128 v[140:143], v140 offset:3072
	ds_read_b128 v[154:157], v166
	ds_read_b128 v[158:161], v166 offset:1024
	ds_read_b128 v[162:165], v166 offset:2048
	ds_read_b128 v[166:169], v166 offset:3072
	v_lshl_add_u64 v[170:171], s[6:7], 0, v[152:153]
	s_add_i32 m0, s25, 0xc000
	ds_read_b128 v[188:191], v186
	ds_read_b128 v[192:195], v186 offset:1024
	ds_read_b128 v[196:199], v186 offset:2048
	ds_read_b128 v[200:203], v186 offset:3072
	ds_read_b128 v[204:207], v186 offset:4096
	ds_read_b128 v[208:211], v186 offset:5120
	ds_read_b128 v[212:215], v186 offset:6144
	ds_read_b128 v[216:219], v186 offset:7168
	global_load_lds_dwordx4 v[170:171], off
	v_lshl_add_u64 v[170:171], s[6:7], 0, v[150:151]
	s_add_i32 m0, s25, 0xe000
	s_nop 0
	global_load_lds_dwordx4 v[170:171], off
	s_waitcnt vmcnt(8) lgkmcnt(0)
	s_setprio 1
	s_barrier
	v_mfma_f32_16x16x32_bf16 v[124:127], v[128:131], v[188:191], v[124:127]
	v_mfma_f32_16x16x32_bf16 v[116:119], v[136:139], v[188:191], v[116:119]
	v_mfma_f32_16x16x32_bf16 v[108:111], v[128:131], v[196:199], v[108:111]
	v_mfma_f32_16x16x32_bf16 v[100:103], v[136:139], v[196:199], v[100:103]
	v_mfma_f32_16x16x32_bf16 v[92:95], v[128:131], v[204:207], v[92:95]
	v_mfma_f32_16x16x32_bf16 v[84:87], v[136:139], v[204:207], v[84:87]
	v_mfma_f32_16x16x32_bf16 v[76:79], v[128:131], v[212:215], v[76:79]
	v_mfma_f32_16x16x32_bf16 v[68:71], v[136:139], v[212:215], v[68:71]
	v_mfma_f32_16x16x32_bf16 v[124:127], v[132:135], v[192:195], v[124:127]
	v_mfma_f32_16x16x32_bf16 v[116:119], v[140:143], v[192:195], v[116:119]
	v_mfma_f32_16x16x32_bf16 v[108:111], v[132:135], v[200:203], v[108:111]
	v_mfma_f32_16x16x32_bf16 v[100:103], v[140:143], v[200:203], v[100:103]
	v_mfma_f32_16x16x32_bf16 v[92:95], v[132:135], v[208:211], v[92:95]
	v_mfma_f32_16x16x32_bf16 v[84:87], v[140:143], v[208:211], v[84:87]
	v_mfma_f32_16x16x32_bf16 v[76:79], v[132:135], v[216:219], v[76:79]
	v_mfma_f32_16x16x32_bf16 v[68:71], v[140:143], v[216:219], v[68:71]
	s_setprio 0
	s_setprio 1
	v_mfma_f32_16x16x32_bf16 v[120:123], v[154:157], v[188:191], v[120:123]
	v_mfma_f32_16x16x32_bf16 v[112:115], v[162:165], v[188:191], v[112:115]
	v_mfma_f32_16x16x32_bf16 v[104:107], v[154:157], v[196:199], v[104:107]
	v_mfma_f32_16x16x32_bf16 v[96:99], v[162:165], v[196:199], v[96:99]
	v_mfma_f32_16x16x32_bf16 v[88:91], v[154:157], v[204:207], v[88:91]
	v_mfma_f32_16x16x32_bf16 v[80:83], v[162:165], v[204:207], v[80:83]
	v_mfma_f32_16x16x32_bf16 v[72:75], v[154:157], v[212:215], v[72:75]
	v_mfma_f32_16x16x32_bf16 v[64:67], v[162:165], v[212:215], v[64:67]
	v_mfma_f32_16x16x32_bf16 v[120:123], v[158:161], v[192:195], v[120:123]
	v_mfma_f32_16x16x32_bf16 v[112:115], v[166:169], v[192:195], v[112:115]
	v_mfma_f32_16x16x32_bf16 v[104:107], v[158:161], v[200:203], v[104:107]
	v_mfma_f32_16x16x32_bf16 v[96:99], v[166:169], v[200:203], v[96:99]
	v_mfma_f32_16x16x32_bf16 v[88:91], v[158:161], v[208:211], v[88:91]
	v_mfma_f32_16x16x32_bf16 v[80:83], v[166:169], v[208:211], v[80:83]
	v_mfma_f32_16x16x32_bf16 v[72:75], v[158:161], v[216:219], v[72:75]
	v_mfma_f32_16x16x32_bf16 v[64:67], v[166:169], v[216:219], v[64:67]
	s_barrier
	s_setprio 0
	s_add_i32 s41, s41, s24
	v_lshl_add_u64 v[170:171], s[18:19], 0, v[146:147]
	s_mov_b32 m0, s41
	ds_read_b128 v[188:191], v186 offset:16384
	ds_read_b128 v[192:195], v186 offset:17408
	ds_read_b128 v[196:199], v186 offset:18432
	ds_read_b128 v[200:203], v186 offset:19456
	ds_read_b128 v[204:207], v186 offset:20480
	ds_read_b128 v[208:211], v186 offset:21504
	ds_read_b128 v[212:215], v186 offset:22528
	ds_read_b128 v[216:219], v186 offset:23552
	global_load_lds_dwordx4 v[170:171], off
	s_add_i32 m0, s41, 0x2000
	s_add_u32 s42, s18, 0x80000
	v_lshl_add_u64 v[228:229], s[18:19], 0, v[144:145]
	s_addc_u32 s43, s19, 0
	s_add_i32 s41, s44, s24
	global_load_lds_dwordx4 v[228:229], off
	v_lshl_add_u64 v[230:231], s[42:43], 0, v[146:147]
	s_mov_b32 m0, s41
	v_lshl_add_u64 v[236:237], s[20:21], 0, v[144:145]
	global_load_lds_dwordx4 v[230:231], off
	v_lshl_add_u64 v[230:231], s[42:43], 0, v[144:145]
	s_add_i32 m0, s41, 0x2000
	s_nop 0
	global_load_lds_dwordx4 v[230:231], off
	v_lshl_add_u64 v[230:231], s[20:21], 0, v[146:147]
	s_mov_b32 m0, s25
	s_nop 0
	global_load_lds_dwordx4 v[230:231], off
	s_mov_b32 m0, s26
	s_nop 0
	global_load_lds_dwordx4 v[236:237], off
	s_waitcnt vmcnt(8) lgkmcnt(0)
	s_setprio 1
	s_barrier
	v_mfma_f32_16x16x32_bf16 v[60:63], v[128:131], v[188:191], v[60:63]
	v_mfma_f32_16x16x32_bf16 v[52:55], v[136:139], v[188:191], v[52:55]
	v_mfma_f32_16x16x32_bf16 v[44:47], v[128:131], v[196:199], v[44:47]
	v_mfma_f32_16x16x32_bf16 v[36:39], v[136:139], v[196:199], v[36:39]
	v_mfma_f32_16x16x32_bf16 v[28:31], v[128:131], v[204:207], v[28:31]
	v_mfma_f32_16x16x32_bf16 v[20:23], v[136:139], v[204:207], v[20:23]
	v_mfma_f32_16x16x32_bf16 v[12:15], v[128:131], v[212:215], v[12:15]
	v_mfma_f32_16x16x32_bf16 v[4:7], v[136:139], v[212:215], v[4:7]
	v_mfma_f32_16x16x32_bf16 v[60:63], v[132:135], v[192:195], v[60:63]
	v_mfma_f32_16x16x32_bf16 v[52:55], v[140:143], v[192:195], v[52:55]
	v_mfma_f32_16x16x32_bf16 v[44:47], v[132:135], v[200:203], v[44:47]
	v_mfma_f32_16x16x32_bf16 v[36:39], v[140:143], v[200:203], v[36:39]
	v_mfma_f32_16x16x32_bf16 v[28:31], v[132:135], v[208:211], v[28:31]
	v_mfma_f32_16x16x32_bf16 v[20:23], v[140:143], v[208:211], v[20:23]
	v_mfma_f32_16x16x32_bf16 v[12:15], v[132:135], v[216:219], v[12:15]
	v_mfma_f32_16x16x32_bf16 v[4:7], v[140:143], v[216:219], v[4:7]
	s_setprio 0
	s_setprio 1
	v_mfma_f32_16x16x32_bf16 v[56:59], v[154:157], v[188:191], v[56:59]
	v_mfma_f32_16x16x32_bf16 v[48:51], v[162:165], v[188:191], v[48:51]
	v_mfma_f32_16x16x32_bf16 v[40:43], v[154:157], v[196:199], v[40:43]
	v_mfma_f32_16x16x32_bf16 v[32:35], v[162:165], v[196:199], v[32:35]
	v_mfma_f32_16x16x32_bf16 v[24:27], v[154:157], v[204:207], v[24:27]
	v_mfma_f32_16x16x32_bf16 v[16:19], v[162:165], v[204:207], v[16:19]
	v_mfma_f32_16x16x32_bf16 v[8:11], v[154:157], v[212:215], v[8:11]
	v_mfma_f32_16x16x32_bf16 v[0:3], v[162:165], v[212:215], v[0:3]
	v_mfma_f32_16x16x32_bf16 v[56:59], v[158:161], v[192:195], v[56:59]
	v_mfma_f32_16x16x32_bf16 v[48:51], v[166:169], v[192:195], v[48:51]
	v_mfma_f32_16x16x32_bf16 v[40:43], v[158:161], v[200:203], v[40:43]
	v_mfma_f32_16x16x32_bf16 v[32:35], v[166:169], v[200:203], v[32:35]
	v_mfma_f32_16x16x32_bf16 v[24:27], v[158:161], v[208:211], v[24:27]
	v_mfma_f32_16x16x32_bf16 v[16:19], v[166:169], v[208:211], v[16:19]
	v_mfma_f32_16x16x32_bf16 v[8:11], v[158:161], v[216:219], v[8:11]
	v_mfma_f32_16x16x32_bf16 v[0:3], v[166:169], v[216:219], v[0:3]
	s_barrier
	s_setprio 0
	s_add_i32 s41, 0, 0x18000
	s_add_i32 s42, 0, 0x1c000
	v_add_u32_e32 v140, s41, v175
	v_add_u32_e32 v166, s42, v175
	ds_read_b128 v[128:131], v140
	ds_read_b128 v[132:135], v140 offset:1024
	ds_read_b128 v[136:139], v140 offset:2048
	ds_read_b128 v[140:143], v140 offset:3072
	ds_read_b128 v[154:157], v166
	ds_read_b128 v[158:161], v166 offset:1024
	ds_read_b128 v[162:165], v166 offset:2048
	ds_read_b128 v[166:169], v166 offset:3072
	s_add_u32 s20, s20, 0x80000
	s_addc_u32 s21, s21, 0
	s_mov_b32 m0, s27
	v_lshl_add_u64 v[238:239], s[20:21], 0, v[146:147]
	ds_read_b128 v[188:191], v186 offset:32768
	ds_read_b128 v[192:195], v186 offset:33792
	ds_read_b128 v[196:199], v186 offset:34816
	ds_read_b128 v[200:203], v186 offset:35840
	ds_read_b128 v[204:207], v186 offset:36864
	ds_read_b128 v[208:211], v186 offset:37888
	ds_read_b128 v[212:215], v186 offset:38912
	ds_read_b128 v[216:219], v186 offset:39936
	global_load_lds_dwordx4 v[238:239], off
	v_lshl_add_u64 v[238:239], s[20:21], 0, v[144:145]
	s_mov_b32 m0, s28
	s_nop 0
	global_load_lds_dwordx4 v[238:239], off
	s_waitcnt vmcnt(8) lgkmcnt(0)
	s_setprio 1
	s_barrier
	v_mfma_f32_16x16x32_bf16 v[124:127], v[128:131], v[188:191], v[124:127]
	v_mfma_f32_16x16x32_bf16 v[116:119], v[136:139], v[188:191], v[116:119]
	v_mfma_f32_16x16x32_bf16 v[108:111], v[128:131], v[196:199], v[108:111]
	v_mfma_f32_16x16x32_bf16 v[100:103], v[136:139], v[196:199], v[100:103]
	v_mfma_f32_16x16x32_bf16 v[92:95], v[128:131], v[204:207], v[92:95]
	v_mfma_f32_16x16x32_bf16 v[84:87], v[136:139], v[204:207], v[84:87]
	v_mfma_f32_16x16x32_bf16 v[76:79], v[128:131], v[212:215], v[76:79]
	v_mfma_f32_16x16x32_bf16 v[68:71], v[136:139], v[212:215], v[68:71]
	v_mfma_f32_16x16x32_bf16 v[124:127], v[132:135], v[192:195], v[124:127]
	v_mfma_f32_16x16x32_bf16 v[116:119], v[140:143], v[192:195], v[116:119]
	v_mfma_f32_16x16x32_bf16 v[108:111], v[132:135], v[200:203], v[108:111]
	v_mfma_f32_16x16x32_bf16 v[100:103], v[140:143], v[200:203], v[100:103]
	v_mfma_f32_16x16x32_bf16 v[92:95], v[132:135], v[208:211], v[92:95]
	v_mfma_f32_16x16x32_bf16 v[84:87], v[140:143], v[208:211], v[84:87]
	v_mfma_f32_16x16x32_bf16 v[76:79], v[132:135], v[216:219], v[76:79]
	v_mfma_f32_16x16x32_bf16 v[68:71], v[140:143], v[216:219], v[68:71]
	s_setprio 0
	s_setprio 1
	v_mfma_f32_16x16x32_bf16 v[120:123], v[154:157], v[188:191], v[120:123]
	v_mfma_f32_16x16x32_bf16 v[112:115], v[162:165], v[188:191], v[112:115]
	v_mfma_f32_16x16x32_bf16 v[104:107], v[154:157], v[196:199], v[104:107]
	v_mfma_f32_16x16x32_bf16 v[96:99], v[162:165], v[196:199], v[96:99]
	v_mfma_f32_16x16x32_bf16 v[88:91], v[154:157], v[204:207], v[88:91]
	v_mfma_f32_16x16x32_bf16 v[80:83], v[162:165], v[204:207], v[80:83]
	v_mfma_f32_16x16x32_bf16 v[72:75], v[154:157], v[212:215], v[72:75]
	v_mfma_f32_16x16x32_bf16 v[64:67], v[162:165], v[212:215], v[64:67]
	v_mfma_f32_16x16x32_bf16 v[120:123], v[158:161], v[192:195], v[120:123]
	v_mfma_f32_16x16x32_bf16 v[112:115], v[166:169], v[192:195], v[112:115]
	v_mfma_f32_16x16x32_bf16 v[104:107], v[158:161], v[200:203], v[104:107]
	v_mfma_f32_16x16x32_bf16 v[96:99], v[166:169], v[200:203], v[96:99]
	v_mfma_f32_16x16x32_bf16 v[88:91], v[158:161], v[208:211], v[88:91]
	v_mfma_f32_16x16x32_bf16 v[80:83], v[166:169], v[208:211], v[80:83]
	v_mfma_f32_16x16x32_bf16 v[72:75], v[158:161], v[216:219], v[72:75]
	v_mfma_f32_16x16x32_bf16 v[64:67], v[166:169], v[216:219], v[64:67]
	s_barrier
	s_setprio 0
	s_add_i32 s20, s41, s24
	v_lshl_add_u64 v[170:171], v[170:171], 0, s[0:1]
	s_mov_b32 m0, s20
	ds_read_b128 v[188:191], v186 offset:49152
	ds_read_b128 v[192:195], v186 offset:50176
	ds_read_b128 v[196:199], v186 offset:51200
	ds_read_b128 v[200:203], v186 offset:52224
	ds_read_b128 v[204:207], v186 offset:53248
	ds_read_b128 v[208:211], v186 offset:54272
	ds_read_b128 v[212:215], v186 offset:55296
	ds_read_b128 v[216:219], v186 offset:56320
	global_load_lds_dwordx4 v[170:171], off
	s_add_i32 m0, s20, 0x2000
	s_add_u32 s18, s18, 0x80080
	v_lshl_add_u64 v[170:171], v[228:229], 0, s[0:1]
	s_addc_u32 s19, s19, 0
	s_add_i32 s20, s42, s24
	global_load_lds_dwordx4 v[170:171], off
	v_lshl_add_u64 v[170:171], s[18:19], 0, v[146:147]
	s_mov_b32 m0, s20
	s_nop 0
	global_load_lds_dwordx4 v[170:171], off
	v_lshl_add_u64 v[170:171], s[18:19], 0, v[144:145]
	s_add_i32 m0, s20, 0x2000
	s_nop 0
	global_load_lds_dwordx4 v[170:171], off
	v_lshl_add_u64 v[170:171], v[230:231], 0, s[0:1]
	s_mov_b32 m0, s29
	s_nop 0
	global_load_lds_dwordx4 v[170:171], off
	v_lshl_add_u64 v[170:171], v[236:237], 0, s[0:1]
	s_mov_b32 m0, s30
	s_nop 0
	global_load_lds_dwordx4 v[170:171], off
	s_waitcnt vmcnt(8) lgkmcnt(0)
	s_setprio 1
	s_barrier
	v_mfma_f32_16x16x32_bf16 v[60:63], v[128:131], v[188:191], v[60:63]
	v_mfma_f32_16x16x32_bf16 v[52:55], v[136:139], v[188:191], v[52:55]
	v_mfma_f32_16x16x32_bf16 v[44:47], v[128:131], v[196:199], v[44:47]
	v_mfma_f32_16x16x32_bf16 v[36:39], v[136:139], v[196:199], v[36:39]
	v_mfma_f32_16x16x32_bf16 v[28:31], v[128:131], v[204:207], v[28:31]
	v_mfma_f32_16x16x32_bf16 v[20:23], v[136:139], v[204:207], v[20:23]
	v_mfma_f32_16x16x32_bf16 v[12:15], v[128:131], v[212:215], v[12:15]
	v_mfma_f32_16x16x32_bf16 v[4:7], v[136:139], v[212:215], v[4:7]
	v_mfma_f32_16x16x32_bf16 v[60:63], v[132:135], v[192:195], v[60:63]
	v_mfma_f32_16x16x32_bf16 v[52:55], v[140:143], v[192:195], v[52:55]
	v_mfma_f32_16x16x32_bf16 v[44:47], v[132:135], v[200:203], v[44:47]
	v_mfma_f32_16x16x32_bf16 v[36:39], v[140:143], v[200:203], v[36:39]
	v_mfma_f32_16x16x32_bf16 v[28:31], v[132:135], v[208:211], v[28:31]
	v_mfma_f32_16x16x32_bf16 v[20:23], v[140:143], v[208:211], v[20:23]
	v_mfma_f32_16x16x32_bf16 v[12:15], v[132:135], v[216:219], v[12:15]
	v_mfma_f32_16x16x32_bf16 v[4:7], v[140:143], v[216:219], v[4:7]
	s_setprio 0
	s_setprio 1
	v_mfma_f32_16x16x32_bf16 v[56:59], v[154:157], v[188:191], v[56:59]
	v_mfma_f32_16x16x32_bf16 v[48:51], v[162:165], v[188:191], v[48:51]
	v_mfma_f32_16x16x32_bf16 v[40:43], v[154:157], v[196:199], v[40:43]
	v_mfma_f32_16x16x32_bf16 v[32:35], v[162:165], v[196:199], v[32:35]
	v_mfma_f32_16x16x32_bf16 v[24:27], v[154:157], v[204:207], v[24:27]
	v_mfma_f32_16x16x32_bf16 v[16:19], v[162:165], v[204:207], v[16:19]
	v_mfma_f32_16x16x32_bf16 v[8:11], v[154:157], v[212:215], v[8:11]
	v_mfma_f32_16x16x32_bf16 v[0:3], v[162:165], v[212:215], v[0:3]
	v_mfma_f32_16x16x32_bf16 v[56:59], v[158:161], v[192:195], v[56:59]
	v_mfma_f32_16x16x32_bf16 v[48:51], v[166:169], v[192:195], v[48:51]
	v_mfma_f32_16x16x32_bf16 v[40:43], v[158:161], v[200:203], v[40:43]
	v_mfma_f32_16x16x32_bf16 v[32:35], v[166:169], v[200:203], v[32:35]
	v_mfma_f32_16x16x32_bf16 v[24:27], v[158:161], v[208:211], v[24:27]
	v_mfma_f32_16x16x32_bf16 v[16:19], v[166:169], v[208:211], v[16:19]
	v_mfma_f32_16x16x32_bf16 v[8:11], v[158:161], v[216:219], v[8:11]
	v_mfma_f32_16x16x32_bf16 v[0:3], v[166:169], v[216:219], v[0:3]
	s_barrier
	s_setprio 0
	s_add_i32 s40, s40, 2
	s_add_u32 s38, s38, 0x100
	s_addc_u32 s39, s39, 0
	s_add_u32 s6, s6, 0x100
	s_addc_u32 s7, s7, 0
	s_cmp_gt_u32 s40, 29
	s_cbranch_scc0 .LBB0_22
	s_and_b64 vcc, exec, s[8:9]
	s_cbranch_vccz .LBB0_25
	s_barrier

.LBB0_50:
	s_add_u32 s24, s2, 0x100
	s_addc_u32 s25, s3, 0
	s_add_i32 s52, 0, 0x10000
	s_cmp_eq_u32 s51, 28
	s_cselect_b32 s29, s19, s25
	s_cselect_b32 s28, s47, s24
	s_cselect_b32 s27, s17, s50
	s_cselect_b32 s26, s48, s49
	s_add_i32 s53, 0, 0x14000
	v_add_u32_e32 v140, s52, v236
	v_add_u32_e32 v156, s53, v236
	s_waitcnt lgkmcnt(0)
	ds_read_b128 v[128:131], v140
	ds_read_b128 v[132:135], v140 offset:1024
	ds_read_b128 v[136:139], v140 offset:2048
	ds_read_b128 v[140:143], v140 offset:3072
	ds_read_b128 v[144:147], v156
	ds_read_b128 v[148:151], v156 offset:1024
	ds_read_b128 v[152:155], v156 offset:2048
	ds_read_b128 v[156:159], v156 offset:3072
	v_lshl_add_u64 v[208:209], s[2:3], 0, v[190:191]
	s_add_i32 m0, s37, 0xc000
	ds_read_b128 v[160:163], v238
	ds_read_b128 v[164:167], v238 offset:1024
	ds_read_b128 v[168:171], v238 offset:2048
	ds_read_b128 v[172:175], v238 offset:3072
	ds_read_b128 v[192:195], v238 offset:4096
	ds_read_b128 v[196:199], v238 offset:5120
	ds_read_b128 v[200:203], v238 offset:6144
	ds_read_b128 v[204:207], v238 offset:7168
	global_load_lds_dwordx4 v[208:209], off
	v_lshl_add_u64 v[208:209], s[2:3], 0, v[188:189]
	s_add_i32 m0, s37, 0xe000
	s_nop 0
	global_load_lds_dwordx4 v[208:209], off
	s_waitcnt vmcnt(8) lgkmcnt(0)
	s_setprio 1
	s_barrier
	v_mfma_f32_16x16x32_bf16 v[124:127], v[128:131], v[160:163], v[124:127]
	v_mfma_f32_16x16x32_bf16 v[120:123], v[136:139], v[160:163], v[120:123]
	v_mfma_f32_16x16x32_bf16 v[108:111], v[128:131], v[168:171], v[108:111]
	v_mfma_f32_16x16x32_bf16 v[104:107], v[136:139], v[168:171], v[104:107]
	v_mfma_f32_16x16x32_bf16 v[92:95], v[128:131], v[192:195], v[92:95]
	v_mfma_f32_16x16x32_bf16 v[88:91], v[136:139], v[192:195], v[88:91]
	v_mfma_f32_16x16x32_bf16 v[76:79], v[128:131], v[200:203], v[76:79]
	v_mfma_f32_16x16x32_bf16 v[72:75], v[136:139], v[200:203], v[72:75]
	v_mfma_f32_16x16x32_bf16 v[124:127], v[132:135], v[164:167], v[124:127]
	v_mfma_f32_16x16x32_bf16 v[120:123], v[140:143], v[164:167], v[120:123]
	v_mfma_f32_16x16x32_bf16 v[108:111], v[132:135], v[172:175], v[108:111]
	v_mfma_f32_16x16x32_bf16 v[104:107], v[140:143], v[172:175], v[104:107]
	v_mfma_f32_16x16x32_bf16 v[92:95], v[132:135], v[196:199], v[92:95]
	v_mfma_f32_16x16x32_bf16 v[88:91], v[140:143], v[196:199], v[88:91]
	v_mfma_f32_16x16x32_bf16 v[76:79], v[132:135], v[204:207], v[76:79]
	v_mfma_f32_16x16x32_bf16 v[72:75], v[140:143], v[204:207], v[72:75]
	s_setprio 0
	s_setprio 1
	v_mfma_f32_16x16x32_bf16 v[116:119], v[144:147], v[160:163], v[116:119]
	v_mfma_f32_16x16x32_bf16 v[112:115], v[152:155], v[160:163], v[112:115]
	v_mfma_f32_16x16x32_bf16 v[100:103], v[144:147], v[168:171], v[100:103]
	v_mfma_f32_16x16x32_bf16 v[96:99], v[152:155], v[168:171], v[96:99]
	v_mfma_f32_16x16x32_bf16 v[84:87], v[144:147], v[192:195], v[84:87]
	v_mfma_f32_16x16x32_bf16 v[80:83], v[152:155], v[192:195], v[80:83]
	v_mfma_f32_16x16x32_bf16 v[68:71], v[144:147], v[200:203], v[68:71]
	v_mfma_f32_16x16x32_bf16 v[64:67], v[152:155], v[200:203], v[64:67]
	v_mfma_f32_16x16x32_bf16 v[116:119], v[148:151], v[164:167], v[116:119]
	v_mfma_f32_16x16x32_bf16 v[112:115], v[156:159], v[164:167], v[112:115]
	v_mfma_f32_16x16x32_bf16 v[100:103], v[148:151], v[172:175], v[100:103]
	v_mfma_f32_16x16x32_bf16 v[96:99], v[156:159], v[172:175], v[96:99]
	v_mfma_f32_16x16x32_bf16 v[84:87], v[148:151], v[196:199], v[84:87]
	v_mfma_f32_16x16x32_bf16 v[80:83], v[156:159], v[196:199], v[80:83]
	v_mfma_f32_16x16x32_bf16 v[68:71], v[148:151], v[204:207], v[68:71]
	v_mfma_f32_16x16x32_bf16 v[64:67], v[156:159], v[204:207], v[64:67]
	s_barrier
	s_setprio 0
	s_add_i32 s2, s52, s34
	v_lshl_add_u64 v[208:209], s[26:27], 0, v[176:177]
	s_mov_b32 m0, s2
	ds_read_b128 v[160:163], v238 offset:16384
	ds_read_b128 v[164:167], v238 offset:17408
	ds_read_b128 v[168:171], v238 offset:18432
	ds_read_b128 v[172:175], v238 offset:19456
	ds_read_b128 v[192:195], v238 offset:20480
	ds_read_b128 v[196:199], v238 offset:21504
	ds_read_b128 v[200:203], v238 offset:22528
	ds_read_b128 v[204:207], v238 offset:23552
	global_load_lds_dwordx4 v[208:209], off
	s_add_i32 m0, s2, 0x2000
	s_add_u32 s2, s26, 0x80000
	v_lshl_add_u64 v[210:211], s[26:27], 0, v[186:187]
	s_addc_u32 s3, s27, 0
	s_add_i32 s52, s53, s34
	global_load_lds_dwordx4 v[210:211], off
	v_lshl_add_u64 v[212:213], s[2:3], 0, v[176:177]
	s_mov_b32 m0, s52
	v_lshl_add_u64 v[214:215], s[28:29], 0, v[186:187]
	global_load_lds_dwordx4 v[212:213], off
	v_lshl_add_u64 v[212:213], s[2:3], 0, v[186:187]
	s_add_i32 m0, s52, 0x2000
	s_nop 0
	global_load_lds_dwordx4 v[212:213], off
	v_lshl_add_u64 v[212:213], s[28:29], 0, v[176:177]
	s_mov_b32 m0, s37
	s_nop 0
	global_load_lds_dwordx4 v[212:213], off
	s_mov_b32 m0, s38
	s_nop 0
	global_load_lds_dwordx4 v[214:215], off
	s_waitcnt vmcnt(8) lgkmcnt(0)
	s_setprio 1
	s_barrier
	v_mfma_f32_16x16x32_bf16 v[60:63], v[128:131], v[160:163], v[60:63]
	v_mfma_f32_16x16x32_bf16 v[56:59], v[136:139], v[160:163], v[56:59]
	v_mfma_f32_16x16x32_bf16 v[44:47], v[128:131], v[168:171], v[44:47]
	v_mfma_f32_16x16x32_bf16 v[40:43], v[136:139], v[168:171], v[40:43]
	v_mfma_f32_16x16x32_bf16 v[28:31], v[128:131], v[192:195], v[28:31]
	v_mfma_f32_16x16x32_bf16 v[24:27], v[136:139], v[192:195], v[24:27]
	v_mfma_f32_16x16x32_bf16 v[12:15], v[128:131], v[200:203], v[12:15]
	v_mfma_f32_16x16x32_bf16 v[8:11], v[136:139], v[200:203], v[8:11]
	v_mfma_f32_16x16x32_bf16 v[60:63], v[132:135], v[164:167], v[60:63]
	v_mfma_f32_16x16x32_bf16 v[56:59], v[140:143], v[164:167], v[56:59]
	v_mfma_f32_16x16x32_bf16 v[44:47], v[132:135], v[172:175], v[44:47]
	v_mfma_f32_16x16x32_bf16 v[40:43], v[140:143], v[172:175], v[40:43]
	v_mfma_f32_16x16x32_bf16 v[28:31], v[132:135], v[196:199], v[28:31]
	v_mfma_f32_16x16x32_bf16 v[24:27], v[140:143], v[196:199], v[24:27]
	v_mfma_f32_16x16x32_bf16 v[12:15], v[132:135], v[204:207], v[12:15]
	v_mfma_f32_16x16x32_bf16 v[8:11], v[140:143], v[204:207], v[8:11]
	s_setprio 0
	s_setprio 1
	v_mfma_f32_16x16x32_bf16 v[52:55], v[144:147], v[160:163], v[52:55]
	v_mfma_f32_16x16x32_bf16 v[48:51], v[152:155], v[160:163], v[48:51]
	v_mfma_f32_16x16x32_bf16 v[36:39], v[144:147], v[168:171], v[36:39]
	v_mfma_f32_16x16x32_bf16 v[32:35], v[152:155], v[168:171], v[32:35]
	v_mfma_f32_16x16x32_bf16 v[20:23], v[144:147], v[192:195], v[20:23]
	v_mfma_f32_16x16x32_bf16 v[16:19], v[152:155], v[192:195], v[16:19]
	v_mfma_f32_16x16x32_bf16 v[4:7], v[144:147], v[200:203], v[4:7]
	v_mfma_f32_16x16x32_bf16 v[0:3], v[152:155], v[200:203], v[0:3]
	v_mfma_f32_16x16x32_bf16 v[52:55], v[148:151], v[164:167], v[52:55]
	v_mfma_f32_16x16x32_bf16 v[48:51], v[156:159], v[164:167], v[48:51]
	v_mfma_f32_16x16x32_bf16 v[36:39], v[148:151], v[172:175], v[36:39]
	v_mfma_f32_16x16x32_bf16 v[32:35], v[156:159], v[172:175], v[32:35]
	v_mfma_f32_16x16x32_bf16 v[20:23], v[148:151], v[196:199], v[20:23]
	v_mfma_f32_16x16x32_bf16 v[16:19], v[156:159], v[196:199], v[16:19]
	v_mfma_f32_16x16x32_bf16 v[4:7], v[148:151], v[204:207], v[4:7]
	v_mfma_f32_16x16x32_bf16 v[0:3], v[156:159], v[204:207], v[0:3]
	s_barrier
	s_setprio 0
	s_add_i32 s52, 0, 0x18000
	s_add_i32 s53, 0, 0x1c000
	v_add_u32_e32 v140, s52, v236
	v_add_u32_e32 v156, s53, v236
	ds_read_b128 v[128:131], v140
	ds_read_b128 v[132:135], v140 offset:1024
	ds_read_b128 v[136:139], v140 offset:2048
	ds_read_b128 v[140:143], v140 offset:3072
	ds_read_b128 v[144:147], v156
	ds_read_b128 v[148:151], v156 offset:1024
	ds_read_b128 v[152:155], v156 offset:2048
	ds_read_b128 v[156:159], v156 offset:3072
	s_add_u32 s2, s28, 0x80000
	s_addc_u32 s3, s29, 0
	s_mov_b32 m0, s39
	v_lshl_add_u64 v[216:217], s[2:3], 0, v[176:177]
	ds_read_b128 v[160:163], v238 offset:32768
	ds_read_b128 v[164:167], v238 offset:33792
	ds_read_b128 v[168:171], v238 offset:34816
	ds_read_b128 v[172:175], v238 offset:35840
	ds_read_b128 v[192:195], v238 offset:36864
	ds_read_b128 v[196:199], v238 offset:37888
	ds_read_b128 v[200:203], v238 offset:38912
	ds_read_b128 v[204:207], v238 offset:39936
	global_load_lds_dwordx4 v[216:217], off
	v_lshl_add_u64 v[216:217], s[2:3], 0, v[186:187]
	s_mov_b32 m0, s40
	s_nop 0
	global_load_lds_dwordx4 v[216:217], off
	s_waitcnt vmcnt(8) lgkmcnt(0)
	s_setprio 1
	s_barrier
	v_mfma_f32_16x16x32_bf16 v[124:127], v[128:131], v[160:163], v[124:127]
	v_mfma_f32_16x16x32_bf16 v[120:123], v[136:139], v[160:163], v[120:123]
	v_mfma_f32_16x16x32_bf16 v[108:111], v[128:131], v[168:171], v[108:111]
	v_mfma_f32_16x16x32_bf16 v[104:107], v[136:139], v[168:171], v[104:107]
	v_mfma_f32_16x16x32_bf16 v[92:95], v[128:131], v[192:195], v[92:95]
	v_mfma_f32_16x16x32_bf16 v[88:91], v[136:139], v[192:195], v[88:91]
	v_mfma_f32_16x16x32_bf16 v[76:79], v[128:131], v[200:203], v[76:79]
	v_mfma_f32_16x16x32_bf16 v[72:75], v[136:139], v[200:203], v[72:75]
	v_mfma_f32_16x16x32_bf16 v[124:127], v[132:135], v[164:167], v[124:127]
	v_mfma_f32_16x16x32_bf16 v[120:123], v[140:143], v[164:167], v[120:123]
	v_mfma_f32_16x16x32_bf16 v[108:111], v[132:135], v[172:175], v[108:111]
	v_mfma_f32_16x16x32_bf16 v[104:107], v[140:143], v[172:175], v[104:107]
	v_mfma_f32_16x16x32_bf16 v[92:95], v[132:135], v[196:199], v[92:95]
	v_mfma_f32_16x16x32_bf16 v[88:91], v[140:143], v[196:199], v[88:91]
	v_mfma_f32_16x16x32_bf16 v[76:79], v[132:135], v[204:207], v[76:79]
	v_mfma_f32_16x16x32_bf16 v[72:75], v[140:143], v[204:207], v[72:75]
	s_setprio 0
	s_setprio 1
	v_mfma_f32_16x16x32_bf16 v[116:119], v[144:147], v[160:163], v[116:119]
	v_mfma_f32_16x16x32_bf16 v[112:115], v[152:155], v[160:163], v[112:115]
	v_mfma_f32_16x16x32_bf16 v[100:103], v[144:147], v[168:171], v[100:103]
	v_mfma_f32_16x16x32_bf16 v[96:99], v[152:155], v[168:171], v[96:99]
	v_mfma_f32_16x16x32_bf16 v[84:87], v[144:147], v[192:195], v[84:87]
	v_mfma_f32_16x16x32_bf16 v[80:83], v[152:155], v[192:195], v[80:83]
	v_mfma_f32_16x16x32_bf16 v[68:71], v[144:147], v[200:203], v[68:71]
	v_mfma_f32_16x16x32_bf16 v[64:67], v[152:155], v[200:203], v[64:67]
	v_mfma_f32_16x16x32_bf16 v[116:119], v[148:151], v[164:167], v[116:119]
	v_mfma_f32_16x16x32_bf16 v[112:115], v[156:159], v[164:167], v[112:115]
	v_mfma_f32_16x16x32_bf16 v[100:103], v[148:151], v[172:175], v[100:103]
	v_mfma_f32_16x16x32_bf16 v[96:99], v[156:159], v[172:175], v[96:99]
	v_mfma_f32_16x16x32_bf16 v[84:87], v[148:151], v[196:199], v[84:87]
	v_mfma_f32_16x16x32_bf16 v[80:83], v[156:159], v[196:199], v[80:83]
	v_mfma_f32_16x16x32_bf16 v[68:71], v[148:151], v[204:207], v[68:71]
	v_mfma_f32_16x16x32_bf16 v[64:67], v[156:159], v[204:207], v[64:67]
	s_barrier
	s_setprio 0
	s_add_i32 s2, s52, s34
	v_lshl_add_u64 v[208:209], v[208:209], 0, s[0:1]
	s_mov_b32 m0, s2
	ds_read_b128 v[160:163], v238 offset:49152
	ds_read_b128 v[164:167], v238 offset:50176
	ds_read_b128 v[168:171], v238 offset:51200
	ds_read_b128 v[172:175], v238 offset:52224
	ds_read_b128 v[192:195], v238 offset:53248
	ds_read_b128 v[196:199], v238 offset:54272
	ds_read_b128 v[200:203], v238 offset:55296
	ds_read_b128 v[204:207], v238 offset:56320
	global_load_lds_dwordx4 v[208:209], off
	s_add_i32 m0, s2, 0x2000
	s_add_u32 s2, s26, 0x80080
	v_lshl_add_u64 v[208:209], v[210:211], 0, s[0:1]
	s_addc_u32 s3, s27, 0
	s_add_i32 s26, s53, s34
	global_load_lds_dwordx4 v[208:209], off
	v_lshl_add_u64 v[208:209], s[2:3], 0, v[176:177]
	s_mov_b32 m0, s26
	s_nop 0
	global_load_lds_dwordx4 v[208:209], off
	v_lshl_add_u64 v[208:209], s[2:3], 0, v[186:187]
	s_add_i32 m0, s26, 0x2000
	s_nop 0
	global_load_lds_dwordx4 v[208:209], off
	v_lshl_add_u64 v[208:209], v[212:213], 0, s[0:1]
	s_mov_b32 m0, s42
	s_nop 0
	global_load_lds_dwordx4 v[208:209], off
	v_lshl_add_u64 v[208:209], v[214:215], 0, s[0:1]
	s_mov_b32 m0, s43
	s_nop 0
	global_load_lds_dwordx4 v[208:209], off
	s_waitcnt vmcnt(8) lgkmcnt(0)
	s_setprio 1
	s_barrier
	v_mfma_f32_16x16x32_bf16 v[60:63], v[128:131], v[160:163], v[60:63]
	v_mfma_f32_16x16x32_bf16 v[56:59], v[136:139], v[160:163], v[56:59]
	v_mfma_f32_16x16x32_bf16 v[44:47], v[128:131], v[168:171], v[44:47]
	v_mfma_f32_16x16x32_bf16 v[40:43], v[136:139], v[168:171], v[40:43]
	v_mfma_f32_16x16x32_bf16 v[28:31], v[128:131], v[192:195], v[28:31]
	v_mfma_f32_16x16x32_bf16 v[24:27], v[136:139], v[192:195], v[24:27]
	v_mfma_f32_16x16x32_bf16 v[12:15], v[128:131], v[200:203], v[12:15]
	v_mfma_f32_16x16x32_bf16 v[8:11], v[136:139], v[200:203], v[8:11]
	v_mfma_f32_16x16x32_bf16 v[60:63], v[132:135], v[164:167], v[60:63]
	v_mfma_f32_16x16x32_bf16 v[56:59], v[140:143], v[164:167], v[56:59]
	v_mfma_f32_16x16x32_bf16 v[44:47], v[132:135], v[172:175], v[44:47]
	v_mfma_f32_16x16x32_bf16 v[40:43], v[140:143], v[172:175], v[40:43]
	v_mfma_f32_16x16x32_bf16 v[28:31], v[132:135], v[196:199], v[28:31]
	v_mfma_f32_16x16x32_bf16 v[24:27], v[140:143], v[196:199], v[24:27]
	v_mfma_f32_16x16x32_bf16 v[12:15], v[132:135], v[204:207], v[12:15]
	v_mfma_f32_16x16x32_bf16 v[8:11], v[140:143], v[204:207], v[8:11]
	s_setprio 0
	s_setprio 1
	v_mfma_f32_16x16x32_bf16 v[52:55], v[144:147], v[160:163], v[52:55]
	v_mfma_f32_16x16x32_bf16 v[48:51], v[152:155], v[160:163], v[48:51]
	v_mfma_f32_16x16x32_bf16 v[36:39], v[144:147], v[168:171], v[36:39]
	v_mfma_f32_16x16x32_bf16 v[32:35], v[152:155], v[168:171], v[32:35]
	v_mfma_f32_16x16x32_bf16 v[20:23], v[144:147], v[192:195], v[20:23]
	v_mfma_f32_16x16x32_bf16 v[16:19], v[152:155], v[192:195], v[16:19]
	v_mfma_f32_16x16x32_bf16 v[4:7], v[144:147], v[200:203], v[4:7]
	v_mfma_f32_16x16x32_bf16 v[0:3], v[152:155], v[200:203], v[0:3]
	v_mfma_f32_16x16x32_bf16 v[52:55], v[148:151], v[164:167], v[52:55]
	v_mfma_f32_16x16x32_bf16 v[48:51], v[156:159], v[164:167], v[48:51]
	v_mfma_f32_16x16x32_bf16 v[36:39], v[148:151], v[172:175], v[36:39]
	v_mfma_f32_16x16x32_bf16 v[32:35], v[156:159], v[172:175], v[32:35]
	v_mfma_f32_16x16x32_bf16 v[20:23], v[148:151], v[196:199], v[20:23]
	v_mfma_f32_16x16x32_bf16 v[16:19], v[156:159], v[196:199], v[16:19]
	v_mfma_f32_16x16x32_bf16 v[4:7], v[148:151], v[204:207], v[4:7]
	v_mfma_f32_16x16x32_bf16 v[0:3], v[156:159], v[204:207], v[0:3]
	s_barrier
	s_setprio 0
	s_add_i32 s51, s51, 2
	s_add_u32 s49, s49, 0x100
	s_addc_u32 s50, s50, 0
	s_cmp_gt_u32 s51, 29
	s_mov_b64 s[2:3], s[24:25]
	s_cbranch_scc0 .LBB0_50
	s_and_b64 vcc, exec, s[12:13]
	s_cbranch_vccz .LBB0_53
	s_barrier

.LBB0_291:
	s_add_u32 s8, s20, 0x100
	s_addc_u32 s9, s21, 0
	s_add_i32 s46, 0, 0x10000
	s_cmpk_eq_i32 s45, 0x54
	s_cselect_b32 s25, s17, s9
	s_cselect_b32 s24, s16, s8
	s_cselect_b32 s23, s19, s44
	s_cselect_b32 s22, s18, s43
	s_add_i32 s47, 0, 0x14000
	v_add_u32_e32 v146, s46, v215
	v_add_u32_e32 v162, s47, v215
	ds_read_b128 v[134:137], v146
	ds_read_b128 v[138:141], v146 offset:1024
	ds_read_b128 v[142:145], v146 offset:2048
	ds_read_b128 v[146:149], v146 offset:3072
	ds_read_b128 v[150:153], v162
	ds_read_b128 v[154:157], v162 offset:1024
	ds_read_b128 v[158:161], v162 offset:2048
	ds_read_b128 v[162:165], v162 offset:3072
	v_lshl_add_u64 v[174:175], s[20:21], 0, v[132:133]
	s_add_i32 m0, s29, 0xc000
	ds_read_b128 v[166:169], v217
	ds_read_b128 v[170:173], v217 offset:1024
	ds_read_b128 v[186:189], v217 offset:2048
	ds_read_b128 v[190:193], v217 offset:3072
	ds_read_b128 v[194:197], v217 offset:4096
	ds_read_b128 v[198:201], v217 offset:5120
	ds_read_b128 v[202:205], v217 offset:6144
	ds_read_b128 v[206:209], v217 offset:7168
	global_load_lds_dwordx4 v[174:175], off
	v_lshl_add_u64 v[174:175], s[20:21], 0, v[130:131]
	s_add_i32 m0, s29, 0xe000
	s_nop 0
	global_load_lds_dwordx4 v[174:175], off
	s_waitcnt vmcnt(8) lgkmcnt(0)
	s_setprio 1
	s_barrier
	v_mfma_f32_16x16x32_bf16 v[124:127], v[134:137], v[166:169], v[124:127]
	v_mfma_f32_16x16x32_bf16 v[120:123], v[142:145], v[166:169], v[120:123]
	v_mfma_f32_16x16x32_bf16 v[108:111], v[134:137], v[186:189], v[108:111]
	v_mfma_f32_16x16x32_bf16 v[104:107], v[142:145], v[186:189], v[104:107]
	v_mfma_f32_16x16x32_bf16 v[92:95], v[134:137], v[194:197], v[92:95]
	v_mfma_f32_16x16x32_bf16 v[88:91], v[142:145], v[194:197], v[88:91]
	v_mfma_f32_16x16x32_bf16 v[76:79], v[134:137], v[202:205], v[76:79]
	v_mfma_f32_16x16x32_bf16 v[72:75], v[142:145], v[202:205], v[72:75]
	v_mfma_f32_16x16x32_bf16 v[124:127], v[138:141], v[170:173], v[124:127]
	v_mfma_f32_16x16x32_bf16 v[120:123], v[146:149], v[170:173], v[120:123]
	v_mfma_f32_16x16x32_bf16 v[108:111], v[138:141], v[190:193], v[108:111]
	v_mfma_f32_16x16x32_bf16 v[104:107], v[146:149], v[190:193], v[104:107]
	v_mfma_f32_16x16x32_bf16 v[92:95], v[138:141], v[198:201], v[92:95]
	v_mfma_f32_16x16x32_bf16 v[88:91], v[146:149], v[198:201], v[88:91]
	v_mfma_f32_16x16x32_bf16 v[76:79], v[138:141], v[206:209], v[76:79]
	v_mfma_f32_16x16x32_bf16 v[72:75], v[146:149], v[206:209], v[72:75]
	s_setprio 0
	s_setprio 1
	v_mfma_f32_16x16x32_bf16 v[116:119], v[150:153], v[166:169], v[116:119]
	v_mfma_f32_16x16x32_bf16 v[112:115], v[158:161], v[166:169], v[112:115]
	v_mfma_f32_16x16x32_bf16 v[100:103], v[150:153], v[186:189], v[100:103]
	v_mfma_f32_16x16x32_bf16 v[96:99], v[158:161], v[186:189], v[96:99]
	v_mfma_f32_16x16x32_bf16 v[84:87], v[150:153], v[194:197], v[84:87]
	v_mfma_f32_16x16x32_bf16 v[80:83], v[158:161], v[194:197], v[80:83]
	v_mfma_f32_16x16x32_bf16 v[68:71], v[150:153], v[202:205], v[68:71]
	v_mfma_f32_16x16x32_bf16 v[64:67], v[158:161], v[202:205], v[64:67]
	v_mfma_f32_16x16x32_bf16 v[116:119], v[154:157], v[170:173], v[116:119]
	v_mfma_f32_16x16x32_bf16 v[112:115], v[162:165], v[170:173], v[112:115]
	v_mfma_f32_16x16x32_bf16 v[100:103], v[154:157], v[190:193], v[100:103]
	v_mfma_f32_16x16x32_bf16 v[96:99], v[162:165], v[190:193], v[96:99]
	v_mfma_f32_16x16x32_bf16 v[84:87], v[154:157], v[198:201], v[84:87]
	v_mfma_f32_16x16x32_bf16 v[80:83], v[162:165], v[198:201], v[80:83]
	v_mfma_f32_16x16x32_bf16 v[68:71], v[154:157], v[206:209], v[68:71]
	v_mfma_f32_16x16x32_bf16 v[64:67], v[162:165], v[206:209], v[64:67]
	s_barrier
	s_setprio 0
	s_add_i32 s20, s46, s28
	v_lshl_add_u64 v[174:175], s[22:23], 0, v[176:177]
	s_mov_b32 m0, s20
	ds_read_b128 v[166:169], v217 offset:16384
	ds_read_b128 v[170:173], v217 offset:17408
	ds_read_b128 v[186:189], v217 offset:18432
	ds_read_b128 v[190:193], v217 offset:19456
	ds_read_b128 v[194:197], v217 offset:20480
	ds_read_b128 v[198:201], v217 offset:21504
	ds_read_b128 v[202:205], v217 offset:22528
	ds_read_b128 v[206:209], v217 offset:23552
	global_load_lds_dwordx4 v[174:175], off
	s_add_i32 m0, s20, 0x2000
	s_add_u32 s20, s22, 0x160000
	v_lshl_add_u64 v[210:211], s[22:23], 0, v[128:129]
	s_addc_u32 s21, s23, 0
	s_add_i32 s46, s47, s28
	global_load_lds_dwordx4 v[210:211], off
	v_lshl_add_u64 v[212:213], s[20:21], 0, v[176:177]
	s_mov_b32 m0, s46
	v_lshl_add_u64 v[218:219], s[24:25], 0, v[128:129]
	global_load_lds_dwordx4 v[212:213], off
	v_lshl_add_u64 v[212:213], s[20:21], 0, v[128:129]
	s_add_i32 m0, s46, 0x2000
	s_nop 0
	global_load_lds_dwordx4 v[212:213], off
	v_lshl_add_u64 v[212:213], s[24:25], 0, v[176:177]
	s_mov_b32 m0, s29
	s_nop 0
	global_load_lds_dwordx4 v[212:213], off
	s_mov_b32 m0, s30
	s_nop 0
	global_load_lds_dwordx4 v[218:219], off
	s_waitcnt vmcnt(8) lgkmcnt(0)
	s_setprio 1
	s_barrier
	v_mfma_f32_16x16x32_bf16 v[60:63], v[134:137], v[166:169], v[60:63]
	v_mfma_f32_16x16x32_bf16 v[56:59], v[142:145], v[166:169], v[56:59]
	v_mfma_f32_16x16x32_bf16 v[44:47], v[134:137], v[186:189], v[44:47]
	v_mfma_f32_16x16x32_bf16 v[40:43], v[142:145], v[186:189], v[40:43]
	v_mfma_f32_16x16x32_bf16 v[28:31], v[134:137], v[194:197], v[28:31]
	v_mfma_f32_16x16x32_bf16 v[24:27], v[142:145], v[194:197], v[24:27]
	v_mfma_f32_16x16x32_bf16 v[12:15], v[134:137], v[202:205], v[12:15]
	v_mfma_f32_16x16x32_bf16 v[8:11], v[142:145], v[202:205], v[8:11]
	v_mfma_f32_16x16x32_bf16 v[60:63], v[138:141], v[170:173], v[60:63]
	v_mfma_f32_16x16x32_bf16 v[56:59], v[146:149], v[170:173], v[56:59]
	v_mfma_f32_16x16x32_bf16 v[44:47], v[138:141], v[190:193], v[44:47]
	v_mfma_f32_16x16x32_bf16 v[40:43], v[146:149], v[190:193], v[40:43]
	v_mfma_f32_16x16x32_bf16 v[28:31], v[138:141], v[198:201], v[28:31]
	v_mfma_f32_16x16x32_bf16 v[24:27], v[146:149], v[198:201], v[24:27]
	v_mfma_f32_16x16x32_bf16 v[12:15], v[138:141], v[206:209], v[12:15]
	v_mfma_f32_16x16x32_bf16 v[8:11], v[146:149], v[206:209], v[8:11]
	s_setprio 0
	s_setprio 1
	v_mfma_f32_16x16x32_bf16 v[52:55], v[150:153], v[166:169], v[52:55]
	v_mfma_f32_16x16x32_bf16 v[48:51], v[158:161], v[166:169], v[48:51]
	v_mfma_f32_16x16x32_bf16 v[36:39], v[150:153], v[186:189], v[36:39]
	v_mfma_f32_16x16x32_bf16 v[32:35], v[158:161], v[186:189], v[32:35]
	v_mfma_f32_16x16x32_bf16 v[20:23], v[150:153], v[194:197], v[20:23]
	v_mfma_f32_16x16x32_bf16 v[16:19], v[158:161], v[194:197], v[16:19]
	v_mfma_f32_16x16x32_bf16 v[4:7], v[150:153], v[202:205], v[4:7]
	v_mfma_f32_16x16x32_bf16 v[0:3], v[158:161], v[202:205], v[0:3]
	v_mfma_f32_16x16x32_bf16 v[52:55], v[154:157], v[170:173], v[52:55]
	v_mfma_f32_16x16x32_bf16 v[48:51], v[162:165], v[170:173], v[48:51]
	v_mfma_f32_16x16x32_bf16 v[36:39], v[154:157], v[190:193], v[36:39]
	v_mfma_f32_16x16x32_bf16 v[32:35], v[162:165], v[190:193], v[32:35]
	v_mfma_f32_16x16x32_bf16 v[20:23], v[154:157], v[198:201], v[20:23]
	v_mfma_f32_16x16x32_bf16 v[16:19], v[162:165], v[198:201], v[16:19]
	v_mfma_f32_16x16x32_bf16 v[4:7], v[154:157], v[206:209], v[4:7]
	v_mfma_f32_16x16x32_bf16 v[0:3], v[162:165], v[206:209], v[0:3]
	s_barrier
	s_setprio 0
	s_add_i32 s46, 0, 0x18000
	s_add_i32 s47, 0, 0x1c000
	v_add_u32_e32 v146, s46, v215
	v_add_u32_e32 v162, s47, v215
	ds_read_b128 v[134:137], v146
	ds_read_b128 v[138:141], v146 offset:1024
	ds_read_b128 v[142:145], v146 offset:2048
	ds_read_b128 v[146:149], v146 offset:3072
	ds_read_b128 v[150:153], v162
	ds_read_b128 v[154:157], v162 offset:1024
	ds_read_b128 v[158:161], v162 offset:2048
	ds_read_b128 v[162:165], v162 offset:3072
	s_add_u32 s20, s24, 0x160000
	s_addc_u32 s21, s25, 0
	s_mov_b32 m0, s31
	v_lshl_add_u64 v[228:229], s[20:21], 0, v[176:177]
	ds_read_b128 v[166:169], v217 offset:32768
	ds_read_b128 v[170:173], v217 offset:33792
	ds_read_b128 v[186:189], v217 offset:34816
	ds_read_b128 v[190:193], v217 offset:35840
	ds_read_b128 v[194:197], v217 offset:36864
	ds_read_b128 v[198:201], v217 offset:37888
	ds_read_b128 v[202:205], v217 offset:38912
	ds_read_b128 v[206:209], v217 offset:39936
	global_load_lds_dwordx4 v[228:229], off
	v_lshl_add_u64 v[228:229], s[20:21], 0, v[128:129]
	s_mov_b32 m0, s34
	s_nop 0
	global_load_lds_dwordx4 v[228:229], off
	s_waitcnt vmcnt(8) lgkmcnt(0)
	s_setprio 1
	s_barrier
	v_mfma_f32_16x16x32_bf16 v[124:127], v[134:137], v[166:169], v[124:127]
	v_mfma_f32_16x16x32_bf16 v[120:123], v[142:145], v[166:169], v[120:123]
	v_mfma_f32_16x16x32_bf16 v[108:111], v[134:137], v[186:189], v[108:111]
	v_mfma_f32_16x16x32_bf16 v[104:107], v[142:145], v[186:189], v[104:107]
	v_mfma_f32_16x16x32_bf16 v[92:95], v[134:137], v[194:197], v[92:95]
	v_mfma_f32_16x16x32_bf16 v[88:91], v[142:145], v[194:197], v[88:91]
	v_mfma_f32_16x16x32_bf16 v[76:79], v[134:137], v[202:205], v[76:79]
	v_mfma_f32_16x16x32_bf16 v[72:75], v[142:145], v[202:205], v[72:75]
	v_mfma_f32_16x16x32_bf16 v[124:127], v[138:141], v[170:173], v[124:127]
	v_mfma_f32_16x16x32_bf16 v[120:123], v[146:149], v[170:173], v[120:123]
	v_mfma_f32_16x16x32_bf16 v[108:111], v[138:141], v[190:193], v[108:111]
	v_mfma_f32_16x16x32_bf16 v[104:107], v[146:149], v[190:193], v[104:107]
	v_mfma_f32_16x16x32_bf16 v[92:95], v[138:141], v[198:201], v[92:95]
	v_mfma_f32_16x16x32_bf16 v[88:91], v[146:149], v[198:201], v[88:91]
	v_mfma_f32_16x16x32_bf16 v[76:79], v[138:141], v[206:209], v[76:79]
	v_mfma_f32_16x16x32_bf16 v[72:75], v[146:149], v[206:209], v[72:75]
	s_setprio 0
	s_setprio 1
	v_mfma_f32_16x16x32_bf16 v[116:119], v[150:153], v[166:169], v[116:119]
	v_mfma_f32_16x16x32_bf16 v[112:115], v[158:161], v[166:169], v[112:115]
	v_mfma_f32_16x16x32_bf16 v[100:103], v[150:153], v[186:189], v[100:103]
	v_mfma_f32_16x16x32_bf16 v[96:99], v[158:161], v[186:189], v[96:99]
	v_mfma_f32_16x16x32_bf16 v[84:87], v[150:153], v[194:197], v[84:87]
	v_mfma_f32_16x16x32_bf16 v[80:83], v[158:161], v[194:197], v[80:83]
	v_mfma_f32_16x16x32_bf16 v[68:71], v[150:153], v[202:205], v[68:71]
	v_mfma_f32_16x16x32_bf16 v[64:67], v[158:161], v[202:205], v[64:67]
	v_mfma_f32_16x16x32_bf16 v[116:119], v[154:157], v[170:173], v[116:119]
	v_mfma_f32_16x16x32_bf16 v[112:115], v[162:165], v[170:173], v[112:115]
	v_mfma_f32_16x16x32_bf16 v[100:103], v[154:157], v[190:193], v[100:103]
	v_mfma_f32_16x16x32_bf16 v[96:99], v[162:165], v[190:193], v[96:99]
	v_mfma_f32_16x16x32_bf16 v[84:87], v[154:157], v[198:201], v[84:87]
	v_mfma_f32_16x16x32_bf16 v[80:83], v[162:165], v[198:201], v[80:83]
	v_mfma_f32_16x16x32_bf16 v[68:71], v[154:157], v[206:209], v[68:71]
	v_mfma_f32_16x16x32_bf16 v[64:67], v[162:165], v[206:209], v[64:67]
	s_barrier
	s_setprio 0
	s_add_i32 s20, s46, s28
	v_lshl_add_u64 v[174:175], v[174:175], 0, s[0:1]
	s_mov_b32 m0, s20
	ds_read_b128 v[166:169], v217 offset:49152
	ds_read_b128 v[170:173], v217 offset:50176
	ds_read_b128 v[186:189], v217 offset:51200
	ds_read_b128 v[190:193], v217 offset:52224
	ds_read_b128 v[194:197], v217 offset:53248
	ds_read_b128 v[198:201], v217 offset:54272
	ds_read_b128 v[202:205], v217 offset:55296
	ds_read_b128 v[206:209], v217 offset:56320
	global_load_lds_dwordx4 v[174:175], off
	s_add_i32 m0, s20, 0x2000
	s_add_u32 s20, s22, 0x160080
	v_lshl_add_u64 v[174:175], v[210:211], 0, s[0:1]
	s_addc_u32 s21, s23, 0
	s_add_i32 s22, s47, s28
	global_load_lds_dwordx4 v[174:175], off
	v_lshl_add_u64 v[174:175], s[20:21], 0, v[176:177]
	s_mov_b32 m0, s22
	s_nop 0
	global_load_lds_dwordx4 v[174:175], off
	v_lshl_add_u64 v[174:175], s[20:21], 0, v[128:129]
	s_add_i32 m0, s22, 0x2000
	s_nop 0
	global_load_lds_dwordx4 v[174:175], off
	v_lshl_add_u64 v[174:175], v[212:213], 0, s[0:1]
	s_mov_b32 m0, s36
	s_nop 0
	global_load_lds_dwordx4 v[174:175], off
	v_lshl_add_u64 v[174:175], v[218:219], 0, s[0:1]
	s_mov_b32 m0, s37
	s_nop 0
	global_load_lds_dwordx4 v[174:175], off
	s_waitcnt vmcnt(8) lgkmcnt(0)
	s_setprio 1
	s_barrier
	v_mfma_f32_16x16x32_bf16 v[60:63], v[134:137], v[166:169], v[60:63]
	v_mfma_f32_16x16x32_bf16 v[56:59], v[142:145], v[166:169], v[56:59]
	v_mfma_f32_16x16x32_bf16 v[44:47], v[134:137], v[186:189], v[44:47]
	v_mfma_f32_16x16x32_bf16 v[40:43], v[142:145], v[186:189], v[40:43]
	v_mfma_f32_16x16x32_bf16 v[28:31], v[134:137], v[194:197], v[28:31]
	v_mfma_f32_16x16x32_bf16 v[24:27], v[142:145], v[194:197], v[24:27]
	v_mfma_f32_16x16x32_bf16 v[12:15], v[134:137], v[202:205], v[12:15]
	v_mfma_f32_16x16x32_bf16 v[8:11], v[142:145], v[202:205], v[8:11]
	v_mfma_f32_16x16x32_bf16 v[60:63], v[138:141], v[170:173], v[60:63]
	v_mfma_f32_16x16x32_bf16 v[56:59], v[146:149], v[170:173], v[56:59]
	v_mfma_f32_16x16x32_bf16 v[44:47], v[138:141], v[190:193], v[44:47]
	v_mfma_f32_16x16x32_bf16 v[40:43], v[146:149], v[190:193], v[40:43]
	v_mfma_f32_16x16x32_bf16 v[28:31], v[138:141], v[198:201], v[28:31]
	v_mfma_f32_16x16x32_bf16 v[24:27], v[146:149], v[198:201], v[24:27]
	v_mfma_f32_16x16x32_bf16 v[12:15], v[138:141], v[206:209], v[12:15]
	v_mfma_f32_16x16x32_bf16 v[8:11], v[146:149], v[206:209], v[8:11]
	s_setprio 0
	s_setprio 1
	v_mfma_f32_16x16x32_bf16 v[52:55], v[150:153], v[166:169], v[52:55]
	v_mfma_f32_16x16x32_bf16 v[48:51], v[158:161], v[166:169], v[48:51]
	v_mfma_f32_16x16x32_bf16 v[36:39], v[150:153], v[186:189], v[36:39]
	v_mfma_f32_16x16x32_bf16 v[32:35], v[158:161], v[186:189], v[32:35]
	v_mfma_f32_16x16x32_bf16 v[20:23], v[150:153], v[194:197], v[20:23]
	v_mfma_f32_16x16x32_bf16 v[16:19], v[158:161], v[194:197], v[16:19]
	v_mfma_f32_16x16x32_bf16 v[4:7], v[150:153], v[202:205], v[4:7]
	v_mfma_f32_16x16x32_bf16 v[0:3], v[158:161], v[202:205], v[0:3]
	v_mfma_f32_16x16x32_bf16 v[52:55], v[154:157], v[170:173], v[52:55]
	v_mfma_f32_16x16x32_bf16 v[48:51], v[162:165], v[170:173], v[48:51]
	v_mfma_f32_16x16x32_bf16 v[36:39], v[154:157], v[190:193], v[36:39]
	v_mfma_f32_16x16x32_bf16 v[32:35], v[162:165], v[190:193], v[32:35]
	v_mfma_f32_16x16x32_bf16 v[20:23], v[154:157], v[198:201], v[20:23]
	v_mfma_f32_16x16x32_bf16 v[16:19], v[162:165], v[198:201], v[16:19]
	v_mfma_f32_16x16x32_bf16 v[4:7], v[154:157], v[206:209], v[4:7]
	v_mfma_f32_16x16x32_bf16 v[0:3], v[162:165], v[206:209], v[0:3]
	s_barrier
	s_setprio 0
	s_add_i32 s45, s45, 2
	s_add_u32 s43, s43, 0x100
	s_addc_u32 s44, s44, 0
	s_cmpk_gt_u32 s45, 0x55
	s_mov_b64 s[20:21], s[8:9]
	s_cbranch_scc0 .LBB0_291
	s_and_b64 vcc, exec, s[14:15]
	s_cbranch_vccz .LBB0_294
	s_barrier

.LBB0_474:
	s_add_u32 s20, s18, 0xfff80080
	s_addc_u32 s21, s19, -1
	s_add_i32 s45, 0, 0x10000
	s_cmp_eq_u32 s44, 28
	s_cselect_b32 s23, s13, s21
	s_cselect_b32 s22, s40, s20
	v_add_u32_e32 v139, s45, v137
	s_cselect_b32 s21, s11, s43
	s_cselect_b32 s20, s41, s42
	s_add_i32 s48, 0, 0x14000
	ds_read_b128 v[140:143], v139
	ds_read_b128 v[144:147], v139 offset:1024
	ds_read_b128 v[148:151], v139 offset:2048
	ds_read_b128 v[152:155], v139 offset:3072
	v_add_u32_e32 v139, s48, v137
	ds_read_b128 v[156:159], v139
	ds_read_b128 v[160:163], v139 offset:1024
	ds_read_b128 v[164:167], v139 offset:2048
	ds_read_b128 v[168:171], v139 offset:3072
	v_lshl_add_u64 v[214:215], s[18:19], 0, v[134:135]
	s_add_i32 m0, s29, 0xc000
	ds_read_b128 v[172:175], v138
	ds_read_b128 v[186:189], v138 offset:1024
	ds_read_b128 v[190:193], v138 offset:2048
	ds_read_b128 v[194:197], v138 offset:3072
	ds_read_b128 v[198:201], v138 offset:4096
	ds_read_b128 v[202:205], v138 offset:5120
	ds_read_b128 v[206:209], v138 offset:6144
	ds_read_b128 v[210:213], v138 offset:7168
	global_load_lds_dwordx4 v[214:215], off
	v_lshl_add_u64 v[214:215], s[18:19], 0, v[132:133]
	s_add_i32 m0, s29, 0xe000
	s_nop 0
	global_load_lds_dwordx4 v[214:215], off
	s_waitcnt vmcnt(8) lgkmcnt(0)
	s_setprio 1
	s_barrier
	v_mfma_f32_16x16x32_bf16 v[124:127], v[140:143], v[172:175], v[124:127]
	v_mfma_f32_16x16x32_bf16 v[120:123], v[148:151], v[172:175], v[120:123]
	v_mfma_f32_16x16x32_bf16 v[116:119], v[140:143], v[190:193], v[116:119]
	v_mfma_f32_16x16x32_bf16 v[108:111], v[148:151], v[190:193], v[108:111]
	v_mfma_f32_16x16x32_bf16 v[100:103], v[140:143], v[198:201], v[100:103]
	v_mfma_f32_16x16x32_bf16 v[92:95], v[148:151], v[198:201], v[92:95]
	v_mfma_f32_16x16x32_bf16 v[84:87], v[140:143], v[206:209], v[84:87]
	v_mfma_f32_16x16x32_bf16 v[76:79], v[148:151], v[206:209], v[76:79]
	v_mfma_f32_16x16x32_bf16 v[124:127], v[144:147], v[186:189], v[124:127]
	v_mfma_f32_16x16x32_bf16 v[120:123], v[152:155], v[186:189], v[120:123]
	v_mfma_f32_16x16x32_bf16 v[116:119], v[144:147], v[194:197], v[116:119]
	v_mfma_f32_16x16x32_bf16 v[108:111], v[152:155], v[194:197], v[108:111]
	v_mfma_f32_16x16x32_bf16 v[100:103], v[144:147], v[202:205], v[100:103]
	v_mfma_f32_16x16x32_bf16 v[92:95], v[152:155], v[202:205], v[92:95]
	v_mfma_f32_16x16x32_bf16 v[84:87], v[144:147], v[210:213], v[84:87]
	v_mfma_f32_16x16x32_bf16 v[76:79], v[152:155], v[210:213], v[76:79]
	s_setprio 0
	s_setprio 1
	v_mfma_f32_16x16x32_bf16 v[112:115], v[156:159], v[172:175], v[112:115]
	v_mfma_f32_16x16x32_bf16 v[104:107], v[164:167], v[172:175], v[104:107]
	v_mfma_f32_16x16x32_bf16 v[96:99], v[156:159], v[190:193], v[96:99]
	v_mfma_f32_16x16x32_bf16 v[88:91], v[164:167], v[190:193], v[88:91]
	v_mfma_f32_16x16x32_bf16 v[80:83], v[156:159], v[198:201], v[80:83]
	v_mfma_f32_16x16x32_bf16 v[72:75], v[164:167], v[198:201], v[72:75]
	v_mfma_f32_16x16x32_bf16 v[68:71], v[156:159], v[206:209], v[68:71]
	v_mfma_f32_16x16x32_bf16 v[64:67], v[164:167], v[206:209], v[64:67]
	v_mfma_f32_16x16x32_bf16 v[112:115], v[160:163], v[186:189], v[112:115]
	v_mfma_f32_16x16x32_bf16 v[104:107], v[168:171], v[186:189], v[104:107]
	v_mfma_f32_16x16x32_bf16 v[96:99], v[160:163], v[194:197], v[96:99]
	v_mfma_f32_16x16x32_bf16 v[88:91], v[168:171], v[194:197], v[88:91]
	v_mfma_f32_16x16x32_bf16 v[80:83], v[160:163], v[202:205], v[80:83]
	v_mfma_f32_16x16x32_bf16 v[72:75], v[168:171], v[202:205], v[72:75]
	v_mfma_f32_16x16x32_bf16 v[68:71], v[160:163], v[210:213], v[68:71]
	v_mfma_f32_16x16x32_bf16 v[64:67], v[168:171], v[210:213], v[64:67]
	s_barrier
	s_setprio 0
	s_add_i32 s45, s45, s28
	v_lshl_add_u64 v[214:215], s[20:21], 0, v[130:131]
	s_mov_b32 m0, s45
	ds_read_b128 v[172:175], v138 offset:16384
	ds_read_b128 v[186:189], v138 offset:17408
	ds_read_b128 v[190:193], v138 offset:18432
	ds_read_b128 v[194:197], v138 offset:19456
	ds_read_b128 v[198:201], v138 offset:20480
	ds_read_b128 v[202:205], v138 offset:21504
	ds_read_b128 v[206:209], v138 offset:22528
	ds_read_b128 v[210:213], v138 offset:23552
	global_load_lds_dwordx4 v[214:215], off
	s_add_i32 m0, s45, 0x2000
	s_add_u32 s46, s20, 0x80000
	v_lshl_add_u64 v[216:217], s[20:21], 0, v[128:129]
	s_addc_u32 s47, s21, 0
	s_add_i32 s45, s48, s28
	global_load_lds_dwordx4 v[216:217], off
	v_lshl_add_u64 v[218:219], s[46:47], 0, v[130:131]
	s_mov_b32 m0, s45
	v_lshl_add_u64 v[228:229], s[22:23], 0, v[128:129]
	global_load_lds_dwordx4 v[218:219], off
	v_lshl_add_u64 v[218:219], s[46:47], 0, v[128:129]
	s_add_i32 m0, s45, 0x2000
	s_nop 0
	global_load_lds_dwordx4 v[218:219], off
	v_lshl_add_u64 v[218:219], s[22:23], 0, v[130:131]
	s_mov_b32 m0, s29
	s_nop 0
	global_load_lds_dwordx4 v[218:219], off
	s_mov_b32 m0, s30
	s_nop 0
	global_load_lds_dwordx4 v[228:229], off
	s_waitcnt vmcnt(8) lgkmcnt(0)
	s_setprio 1
	s_barrier
	v_mfma_f32_16x16x32_bf16 v[60:63], v[140:143], v[172:175], v[60:63]
	v_mfma_f32_16x16x32_bf16 v[56:59], v[148:151], v[172:175], v[56:59]
	v_mfma_f32_16x16x32_bf16 v[52:55], v[140:143], v[190:193], v[52:55]
	v_mfma_f32_16x16x32_bf16 v[44:47], v[148:151], v[190:193], v[44:47]
	v_mfma_f32_16x16x32_bf16 v[36:39], v[140:143], v[198:201], v[36:39]
	v_mfma_f32_16x16x32_bf16 v[28:31], v[148:151], v[198:201], v[28:31]
	v_mfma_f32_16x16x32_bf16 v[20:23], v[140:143], v[206:209], v[20:23]
	v_mfma_f32_16x16x32_bf16 v[12:15], v[148:151], v[206:209], v[12:15]
	v_mfma_f32_16x16x32_bf16 v[60:63], v[144:147], v[186:189], v[60:63]
	v_mfma_f32_16x16x32_bf16 v[56:59], v[152:155], v[186:189], v[56:59]
	v_mfma_f32_16x16x32_bf16 v[52:55], v[144:147], v[194:197], v[52:55]
	v_mfma_f32_16x16x32_bf16 v[44:47], v[152:155], v[194:197], v[44:47]
	v_mfma_f32_16x16x32_bf16 v[36:39], v[144:147], v[202:205], v[36:39]
	v_mfma_f32_16x16x32_bf16 v[28:31], v[152:155], v[202:205], v[28:31]
	v_mfma_f32_16x16x32_bf16 v[20:23], v[144:147], v[210:213], v[20:23]
	v_mfma_f32_16x16x32_bf16 v[12:15], v[152:155], v[210:213], v[12:15]
	s_setprio 0
	s_setprio 1
	v_mfma_f32_16x16x32_bf16 v[48:51], v[156:159], v[172:175], v[48:51]
	v_mfma_f32_16x16x32_bf16 v[40:43], v[164:167], v[172:175], v[40:43]
	v_mfma_f32_16x16x32_bf16 v[32:35], v[156:159], v[190:193], v[32:35]
	v_mfma_f32_16x16x32_bf16 v[24:27], v[164:167], v[190:193], v[24:27]
	v_mfma_f32_16x16x32_bf16 v[16:19], v[156:159], v[198:201], v[16:19]
	v_mfma_f32_16x16x32_bf16 v[8:11], v[164:167], v[198:201], v[8:11]
	v_mfma_f32_16x16x32_bf16 v[4:7], v[156:159], v[206:209], v[4:7]
	v_mfma_f32_16x16x32_bf16 v[0:3], v[164:167], v[206:209], v[0:3]
	v_mfma_f32_16x16x32_bf16 v[48:51], v[160:163], v[186:189], v[48:51]
	v_mfma_f32_16x16x32_bf16 v[40:43], v[168:171], v[186:189], v[40:43]
	v_mfma_f32_16x16x32_bf16 v[32:35], v[160:163], v[194:197], v[32:35]
	v_mfma_f32_16x16x32_bf16 v[24:27], v[168:171], v[194:197], v[24:27]
	v_mfma_f32_16x16x32_bf16 v[16:19], v[160:163], v[202:205], v[16:19]
	v_mfma_f32_16x16x32_bf16 v[8:11], v[168:171], v[202:205], v[8:11]
	v_mfma_f32_16x16x32_bf16 v[4:7], v[160:163], v[210:213], v[4:7]
	v_mfma_f32_16x16x32_bf16 v[0:3], v[168:171], v[210:213], v[0:3]
	s_barrier
	s_setprio 0
	s_add_i32 s45, 0, 0x18000
	v_add_u32_e32 v139, s45, v137
	s_add_i32 s46, 0, 0x1c000
	ds_read_b128 v[140:143], v139
	ds_read_b128 v[144:147], v139 offset:1024
	ds_read_b128 v[148:151], v139 offset:2048
	ds_read_b128 v[152:155], v139 offset:3072
	v_add_u32_e32 v139, s46, v137
	ds_read_b128 v[156:159], v139
	ds_read_b128 v[160:163], v139 offset:1024
	ds_read_b128 v[164:167], v139 offset:2048
	ds_read_b128 v[168:171], v139 offset:3072
	s_add_u32 s22, s22, 0x80000
	s_addc_u32 s23, s23, 0
	s_mov_b32 m0, s31
	v_lshl_add_u64 v[230:231], s[22:23], 0, v[130:131]
	ds_read_b128 v[172:175], v138 offset:32768
	ds_read_b128 v[186:189], v138 offset:33792
	ds_read_b128 v[190:193], v138 offset:34816
	ds_read_b128 v[194:197], v138 offset:35840
	ds_read_b128 v[198:201], v138 offset:36864
	ds_read_b128 v[202:205], v138 offset:37888
	ds_read_b128 v[206:209], v138 offset:38912
	ds_read_b128 v[210:213], v138 offset:39936
	global_load_lds_dwordx4 v[230:231], off
	v_lshl_add_u64 v[230:231], s[22:23], 0, v[128:129]
	s_mov_b32 m0, s34
	s_nop 0
	global_load_lds_dwordx4 v[230:231], off
	s_waitcnt vmcnt(8) lgkmcnt(0)
	s_setprio 1
	s_barrier
	v_mfma_f32_16x16x32_bf16 v[124:127], v[140:143], v[172:175], v[124:127]
	v_mfma_f32_16x16x32_bf16 v[120:123], v[148:151], v[172:175], v[120:123]
	v_mfma_f32_16x16x32_bf16 v[116:119], v[140:143], v[190:193], v[116:119]
	v_mfma_f32_16x16x32_bf16 v[108:111], v[148:151], v[190:193], v[108:111]
	v_mfma_f32_16x16x32_bf16 v[100:103], v[140:143], v[198:201], v[100:103]
	v_mfma_f32_16x16x32_bf16 v[92:95], v[148:151], v[198:201], v[92:95]
	v_mfma_f32_16x16x32_bf16 v[84:87], v[140:143], v[206:209], v[84:87]
	v_mfma_f32_16x16x32_bf16 v[76:79], v[148:151], v[206:209], v[76:79]
	v_mfma_f32_16x16x32_bf16 v[124:127], v[144:147], v[186:189], v[124:127]
	v_mfma_f32_16x16x32_bf16 v[120:123], v[152:155], v[186:189], v[120:123]
	v_mfma_f32_16x16x32_bf16 v[116:119], v[144:147], v[194:197], v[116:119]
	v_mfma_f32_16x16x32_bf16 v[108:111], v[152:155], v[194:197], v[108:111]
	v_mfma_f32_16x16x32_bf16 v[100:103], v[144:147], v[202:205], v[100:103]
	v_mfma_f32_16x16x32_bf16 v[92:95], v[152:155], v[202:205], v[92:95]
	v_mfma_f32_16x16x32_bf16 v[84:87], v[144:147], v[210:213], v[84:87]
	v_mfma_f32_16x16x32_bf16 v[76:79], v[152:155], v[210:213], v[76:79]
	s_setprio 0
	s_setprio 1
	v_mfma_f32_16x16x32_bf16 v[112:115], v[156:159], v[172:175], v[112:115]
	v_mfma_f32_16x16x32_bf16 v[104:107], v[164:167], v[172:175], v[104:107]
	v_mfma_f32_16x16x32_bf16 v[96:99], v[156:159], v[190:193], v[96:99]
	v_mfma_f32_16x16x32_bf16 v[88:91], v[164:167], v[190:193], v[88:91]
	v_mfma_f32_16x16x32_bf16 v[80:83], v[156:159], v[198:201], v[80:83]
	v_mfma_f32_16x16x32_bf16 v[72:75], v[164:167], v[198:201], v[72:75]
	v_mfma_f32_16x16x32_bf16 v[68:71], v[156:159], v[206:209], v[68:71]
	v_mfma_f32_16x16x32_bf16 v[64:67], v[164:167], v[206:209], v[64:67]
	v_mfma_f32_16x16x32_bf16 v[112:115], v[160:163], v[186:189], v[112:115]
	v_mfma_f32_16x16x32_bf16 v[104:107], v[168:171], v[186:189], v[104:107]
	v_mfma_f32_16x16x32_bf16 v[96:99], v[160:163], v[194:197], v[96:99]
	v_mfma_f32_16x16x32_bf16 v[88:91], v[168:171], v[194:197], v[88:91]
	v_mfma_f32_16x16x32_bf16 v[80:83], v[160:163], v[202:205], v[80:83]
	v_mfma_f32_16x16x32_bf16 v[72:75], v[168:171], v[202:205], v[72:75]
	v_mfma_f32_16x16x32_bf16 v[68:71], v[160:163], v[210:213], v[68:71]
	v_mfma_f32_16x16x32_bf16 v[64:67], v[168:171], v[210:213], v[64:67]
	s_barrier
	s_setprio 0
	s_add_i32 s22, s45, s28
	v_lshl_add_u64 v[214:215], v[214:215], 0, s[0:1]
	s_mov_b32 m0, s22
	ds_read_b128 v[172:175], v138 offset:49152
	ds_read_b128 v[186:189], v138 offset:50176
	ds_read_b128 v[190:193], v138 offset:51200
	ds_read_b128 v[194:197], v138 offset:52224
	ds_read_b128 v[198:201], v138 offset:53248
	ds_read_b128 v[202:205], v138 offset:54272
	ds_read_b128 v[206:209], v138 offset:55296
	ds_read_b128 v[210:213], v138 offset:56320
	global_load_lds_dwordx4 v[214:215], off
	s_add_i32 m0, s22, 0x2000
	s_add_u32 s20, s20, 0x80080
	v_lshl_add_u64 v[214:215], v[216:217], 0, s[0:1]
	s_addc_u32 s21, s21, 0
	s_add_i32 s22, s46, s28
	global_load_lds_dwordx4 v[214:215], off
	v_lshl_add_u64 v[214:215], s[20:21], 0, v[130:131]
	s_mov_b32 m0, s22
	s_nop 0
	global_load_lds_dwordx4 v[214:215], off
	v_lshl_add_u64 v[214:215], s[20:21], 0, v[128:129]
	s_add_i32 m0, s22, 0x2000
	s_nop 0
	global_load_lds_dwordx4 v[214:215], off
	v_lshl_add_u64 v[214:215], v[218:219], 0, s[0:1]
	s_mov_b32 m0, s35
	s_nop 0
	global_load_lds_dwordx4 v[214:215], off
	v_lshl_add_u64 v[214:215], v[228:229], 0, s[0:1]
	s_mov_b32 m0, s36
	s_nop 0
	global_load_lds_dwordx4 v[214:215], off
	s_waitcnt vmcnt(8) lgkmcnt(0)
	s_setprio 1
	s_barrier
	v_mfma_f32_16x16x32_bf16 v[60:63], v[140:143], v[172:175], v[60:63]
	v_mfma_f32_16x16x32_bf16 v[56:59], v[148:151], v[172:175], v[56:59]
	v_mfma_f32_16x16x32_bf16 v[52:55], v[140:143], v[190:193], v[52:55]
	v_mfma_f32_16x16x32_bf16 v[44:47], v[148:151], v[190:193], v[44:47]
	v_mfma_f32_16x16x32_bf16 v[36:39], v[140:143], v[198:201], v[36:39]
	v_mfma_f32_16x16x32_bf16 v[28:31], v[148:151], v[198:201], v[28:31]
	v_mfma_f32_16x16x32_bf16 v[20:23], v[140:143], v[206:209], v[20:23]
	v_mfma_f32_16x16x32_bf16 v[12:15], v[148:151], v[206:209], v[12:15]
	v_mfma_f32_16x16x32_bf16 v[60:63], v[144:147], v[186:189], v[60:63]
	v_mfma_f32_16x16x32_bf16 v[56:59], v[152:155], v[186:189], v[56:59]
	v_mfma_f32_16x16x32_bf16 v[52:55], v[144:147], v[194:197], v[52:55]
	v_mfma_f32_16x16x32_bf16 v[44:47], v[152:155], v[194:197], v[44:47]
	v_mfma_f32_16x16x32_bf16 v[36:39], v[144:147], v[202:205], v[36:39]
	v_mfma_f32_16x16x32_bf16 v[28:31], v[152:155], v[202:205], v[28:31]
	v_mfma_f32_16x16x32_bf16 v[20:23], v[144:147], v[210:213], v[20:23]
	v_mfma_f32_16x16x32_bf16 v[12:15], v[152:155], v[210:213], v[12:15]
	s_setprio 0
	s_setprio 1
	v_mfma_f32_16x16x32_bf16 v[48:51], v[156:159], v[172:175], v[48:51]
	v_mfma_f32_16x16x32_bf16 v[40:43], v[164:167], v[172:175], v[40:43]
	v_mfma_f32_16x16x32_bf16 v[32:35], v[156:159], v[190:193], v[32:35]
	v_mfma_f32_16x16x32_bf16 v[24:27], v[164:167], v[190:193], v[24:27]
	v_mfma_f32_16x16x32_bf16 v[16:19], v[156:159], v[198:201], v[16:19]
	v_mfma_f32_16x16x32_bf16 v[8:11], v[164:167], v[198:201], v[8:11]
	v_mfma_f32_16x16x32_bf16 v[4:7], v[156:159], v[206:209], v[4:7]
	v_mfma_f32_16x16x32_bf16 v[0:3], v[164:167], v[206:209], v[0:3]
	v_mfma_f32_16x16x32_bf16 v[48:51], v[160:163], v[186:189], v[48:51]
	v_mfma_f32_16x16x32_bf16 v[40:43], v[168:171], v[186:189], v[40:43]
	v_mfma_f32_16x16x32_bf16 v[32:35], v[160:163], v[194:197], v[32:35]
	v_mfma_f32_16x16x32_bf16 v[24:27], v[168:171], v[194:197], v[24:27]
	v_mfma_f32_16x16x32_bf16 v[16:19], v[160:163], v[202:205], v[16:19]
	v_mfma_f32_16x16x32_bf16 v[8:11], v[168:171], v[202:205], v[8:11]
	v_mfma_f32_16x16x32_bf16 v[4:7], v[160:163], v[210:213], v[4:7]
	v_mfma_f32_16x16x32_bf16 v[0:3], v[168:171], v[210:213], v[0:3]
	s_barrier
	s_setprio 0
	s_add_i32 s44, s44, 2
	s_add_u32 s42, s42, 0x100
	s_addc_u32 s43, s43, 0
	s_add_u32 s18, s18, 0x100
	s_addc_u32 s19, s19, 0
	s_cmp_gt_u32 s44, 29
	s_cbranch_scc0 .LBB0_474
	s_and_b64 vcc, exec, s[6:7]
	s_movk_i32 s22, 0x1000
	s_cbranch_vccz .LBB0_477
	s_barrier

.LBB0_490:
	s_add_u32 s28, s6, 0xfff80080
	s_addc_u32 s29, s7, -1
	s_add_i32 s52, 0, 0x10000
	s_cmp_eq_u32 s51, 28
	s_cselect_b32 s31, s23, s29
	s_cselect_b32 s30, s47, s28
	s_cselect_b32 s29, s21, s50
	s_cselect_b32 s28, s48, s49
	s_add_i32 s54, 0, 0x14000
	v_add_u32_e32 v140, s52, v187
	s_waitcnt lgkmcnt(0)
	v_add_u32_e32 v168, s54, v187
	ds_read_b128 v[128:131], v140
	ds_read_b128 v[132:135], v140 offset:1024
	ds_read_b128 v[136:139], v140 offset:2048
	ds_read_b128 v[140:143], v140 offset:3072
	ds_read_b128 v[156:159], v168
	ds_read_b128 v[160:163], v168 offset:1024
	ds_read_b128 v[164:167], v168 offset:2048
	ds_read_b128 v[168:171], v168 offset:3072
	v_lshl_add_u64 v[172:173], s[6:7], 0, v[154:155]
	s_add_i32 m0, s39, 0xc000
	ds_read_b128 v[190:193], v189
	ds_read_b128 v[194:197], v189 offset:1024
	ds_read_b128 v[198:201], v189 offset:2048
	ds_read_b128 v[202:205], v189 offset:3072
	ds_read_b128 v[206:209], v189 offset:4096
	ds_read_b128 v[210:213], v189 offset:5120
	ds_read_b128 v[214:217], v189 offset:6144
	ds_read_b128 v[236:239], v189 offset:7168
	global_load_lds_dwordx4 v[172:173], off
	v_lshl_add_u64 v[172:173], s[6:7], 0, v[152:153]
	s_add_i32 m0, s39, 0xe000
	s_nop 0
	global_load_lds_dwordx4 v[172:173], off
	s_waitcnt vmcnt(8) lgkmcnt(0)
	s_setprio 1
	s_barrier
	v_mfma_f32_16x16x32_bf16 v[124:127], v[128:131], v[190:193], v[124:127]
	v_mfma_f32_16x16x32_bf16 v[120:123], v[136:139], v[190:193], v[120:123]
	v_mfma_f32_16x16x32_bf16 v[108:111], v[128:131], v[198:201], v[108:111]
	v_mfma_f32_16x16x32_bf16 v[104:107], v[136:139], v[198:201], v[104:107]
	v_mfma_f32_16x16x32_bf16 v[92:95], v[128:131], v[206:209], v[92:95]
	v_mfma_f32_16x16x32_bf16 v[88:91], v[136:139], v[206:209], v[88:91]
	v_mfma_f32_16x16x32_bf16 v[76:79], v[128:131], v[214:217], v[76:79]
	v_mfma_f32_16x16x32_bf16 v[72:75], v[136:139], v[214:217], v[72:75]
	v_mfma_f32_16x16x32_bf16 v[124:127], v[132:135], v[194:197], v[124:127]
	v_mfma_f32_16x16x32_bf16 v[120:123], v[140:143], v[194:197], v[120:123]
	v_mfma_f32_16x16x32_bf16 v[108:111], v[132:135], v[202:205], v[108:111]
	v_mfma_f32_16x16x32_bf16 v[104:107], v[140:143], v[202:205], v[104:107]
	v_mfma_f32_16x16x32_bf16 v[92:95], v[132:135], v[210:213], v[92:95]
	v_mfma_f32_16x16x32_bf16 v[88:91], v[140:143], v[210:213], v[88:91]
	v_mfma_f32_16x16x32_bf16 v[76:79], v[132:135], v[236:239], v[76:79]
	v_mfma_f32_16x16x32_bf16 v[72:75], v[140:143], v[236:239], v[72:75]
	s_setprio 0
	s_setprio 1
	v_mfma_f32_16x16x32_bf16 v[116:119], v[156:159], v[190:193], v[116:119]
	v_mfma_f32_16x16x32_bf16 v[112:115], v[164:167], v[190:193], v[112:115]
	v_mfma_f32_16x16x32_bf16 v[100:103], v[156:159], v[198:201], v[100:103]
	v_mfma_f32_16x16x32_bf16 v[96:99], v[164:167], v[198:201], v[96:99]
	v_mfma_f32_16x16x32_bf16 v[84:87], v[156:159], v[206:209], v[84:87]
	v_mfma_f32_16x16x32_bf16 v[80:83], v[164:167], v[206:209], v[80:83]
	v_mfma_f32_16x16x32_bf16 v[68:71], v[156:159], v[214:217], v[68:71]
	v_mfma_f32_16x16x32_bf16 v[64:67], v[164:167], v[214:217], v[64:67]
	v_mfma_f32_16x16x32_bf16 v[116:119], v[160:163], v[194:197], v[116:119]
	v_mfma_f32_16x16x32_bf16 v[112:115], v[168:171], v[194:197], v[112:115]
	v_mfma_f32_16x16x32_bf16 v[100:103], v[160:163], v[202:205], v[100:103]
	v_mfma_f32_16x16x32_bf16 v[96:99], v[168:171], v[202:205], v[96:99]
	v_mfma_f32_16x16x32_bf16 v[84:87], v[160:163], v[210:213], v[84:87]
	v_mfma_f32_16x16x32_bf16 v[80:83], v[168:171], v[210:213], v[80:83]
	v_mfma_f32_16x16x32_bf16 v[68:71], v[160:163], v[236:239], v[68:71]
	v_mfma_f32_16x16x32_bf16 v[64:67], v[168:171], v[236:239], v[64:67]
	s_barrier
	s_setprio 0
	s_add_i32 s52, s52, s38
	v_lshl_add_u64 v[172:173], s[28:29], 0, v[146:147]
	s_mov_b32 m0, s52
	ds_read_b128 v[190:193], v189 offset:16384
	ds_read_b128 v[194:197], v189 offset:17408
	ds_read_b128 v[198:201], v189 offset:18432
	ds_read_b128 v[202:205], v189 offset:19456
	ds_read_b128 v[206:209], v189 offset:20480
	ds_read_b128 v[210:213], v189 offset:21504
	ds_read_b128 v[214:217], v189 offset:22528
	ds_read_b128 v[236:239], v189 offset:23552
	global_load_lds_dwordx4 v[172:173], off
	s_add_i32 m0, s52, 0x2000
	s_add_u32 s52, s28, 0x80000
	v_lshl_add_u64 v[218:219], s[28:29], 0, v[144:145]
	s_addc_u32 s53, s29, 0
	s_add_i32 s54, s54, s38
	global_load_lds_dwordx4 v[218:219], off
	v_lshl_add_u64 v[228:229], s[52:53], 0, v[146:147]
	s_mov_b32 m0, s54
	v_lshl_add_u64 v[230:231], s[30:31], 0, v[144:145]
	global_load_lds_dwordx4 v[228:229], off
	v_lshl_add_u64 v[228:229], s[52:53], 0, v[144:145]
	s_add_i32 m0, s54, 0x2000
	s_nop 0
	global_load_lds_dwordx4 v[228:229], off
	v_lshl_add_u64 v[228:229], s[30:31], 0, v[146:147]
	s_mov_b32 m0, s39
	s_nop 0
	global_load_lds_dwordx4 v[228:229], off
	s_mov_b32 m0, s40
	s_nop 0
	global_load_lds_dwordx4 v[230:231], off
	s_waitcnt vmcnt(8) lgkmcnt(0)
	s_setprio 1
	s_barrier
	v_mfma_f32_16x16x32_bf16 v[60:63], v[128:131], v[190:193], v[60:63]
	v_mfma_f32_16x16x32_bf16 v[56:59], v[136:139], v[190:193], v[56:59]
	v_mfma_f32_16x16x32_bf16 v[44:47], v[128:131], v[198:201], v[44:47]
	v_mfma_f32_16x16x32_bf16 v[40:43], v[136:139], v[198:201], v[40:43]
	v_mfma_f32_16x16x32_bf16 v[28:31], v[128:131], v[206:209], v[28:31]
	v_mfma_f32_16x16x32_bf16 v[24:27], v[136:139], v[206:209], v[24:27]
	v_mfma_f32_16x16x32_bf16 v[12:15], v[128:131], v[214:217], v[12:15]
	v_mfma_f32_16x16x32_bf16 v[8:11], v[136:139], v[214:217], v[8:11]
	v_mfma_f32_16x16x32_bf16 v[60:63], v[132:135], v[194:197], v[60:63]
	v_mfma_f32_16x16x32_bf16 v[56:59], v[140:143], v[194:197], v[56:59]
	v_mfma_f32_16x16x32_bf16 v[44:47], v[132:135], v[202:205], v[44:47]
	v_mfma_f32_16x16x32_bf16 v[40:43], v[140:143], v[202:205], v[40:43]
	v_mfma_f32_16x16x32_bf16 v[28:31], v[132:135], v[210:213], v[28:31]
	v_mfma_f32_16x16x32_bf16 v[24:27], v[140:143], v[210:213], v[24:27]
	v_mfma_f32_16x16x32_bf16 v[12:15], v[132:135], v[236:239], v[12:15]
	v_mfma_f32_16x16x32_bf16 v[8:11], v[140:143], v[236:239], v[8:11]
	s_setprio 0
	s_setprio 1
	v_mfma_f32_16x16x32_bf16 v[52:55], v[156:159], v[190:193], v[52:55]
	v_mfma_f32_16x16x32_bf16 v[48:51], v[164:167], v[190:193], v[48:51]
	v_mfma_f32_16x16x32_bf16 v[36:39], v[156:159], v[198:201], v[36:39]
	v_mfma_f32_16x16x32_bf16 v[32:35], v[164:167], v[198:201], v[32:35]
	v_mfma_f32_16x16x32_bf16 v[20:23], v[156:159], v[206:209], v[20:23]
	v_mfma_f32_16x16x32_bf16 v[16:19], v[164:167], v[206:209], v[16:19]
	v_mfma_f32_16x16x32_bf16 v[4:7], v[156:159], v[214:217], v[4:7]
	v_mfma_f32_16x16x32_bf16 v[0:3], v[164:167], v[214:217], v[0:3]
	v_mfma_f32_16x16x32_bf16 v[52:55], v[160:163], v[194:197], v[52:55]
	v_mfma_f32_16x16x32_bf16 v[48:51], v[168:171], v[194:197], v[48:51]
	v_mfma_f32_16x16x32_bf16 v[36:39], v[160:163], v[202:205], v[36:39]
	v_mfma_f32_16x16x32_bf16 v[32:35], v[168:171], v[202:205], v[32:35]
	v_mfma_f32_16x16x32_bf16 v[20:23], v[160:163], v[210:213], v[20:23]
	v_mfma_f32_16x16x32_bf16 v[16:19], v[168:171], v[210:213], v[16:19]
	v_mfma_f32_16x16x32_bf16 v[4:7], v[160:163], v[236:239], v[4:7]
	v_mfma_f32_16x16x32_bf16 v[0:3], v[168:171], v[236:239], v[0:3]
	s_barrier
	s_setprio 0
	s_add_i32 s52, 0, 0x18000
	s_add_i32 s53, 0, 0x1c000
	v_add_u32_e32 v140, s52, v187
	v_add_u32_e32 v168, s53, v187
	ds_read_b128 v[128:131], v140
	ds_read_b128 v[132:135], v140 offset:1024
	ds_read_b128 v[136:139], v140 offset:2048
	ds_read_b128 v[140:143], v140 offset:3072
	ds_read_b128 v[156:159], v168
	ds_read_b128 v[160:163], v168 offset:1024
	ds_read_b128 v[164:167], v168 offset:2048
	ds_read_b128 v[168:171], v168 offset:3072
	s_add_u32 s30, s30, 0x80000
	s_addc_u32 s31, s31, 0
	s_mov_b32 m0, s41
	v_lshl_add_u64 v[240:241], s[30:31], 0, v[146:147]
	ds_read_b128 v[190:193], v189 offset:32768
	ds_read_b128 v[194:197], v189 offset:33792
	ds_read_b128 v[198:201], v189 offset:34816
	ds_read_b128 v[202:205], v189 offset:35840
	ds_read_b128 v[206:209], v189 offset:36864
	ds_read_b128 v[210:213], v189 offset:37888
	ds_read_b128 v[214:217], v189 offset:38912
	ds_read_b128 v[236:239], v189 offset:39936
	global_load_lds_dwordx4 v[240:241], off
	v_lshl_add_u64 v[240:241], s[30:31], 0, v[144:145]
	s_mov_b32 m0, s42
	s_nop 0
	global_load_lds_dwordx4 v[240:241], off
	s_waitcnt vmcnt(8) lgkmcnt(0)
	s_setprio 1
	s_barrier
	v_mfma_f32_16x16x32_bf16 v[124:127], v[128:131], v[190:193], v[124:127]
	v_mfma_f32_16x16x32_bf16 v[120:123], v[136:139], v[190:193], v[120:123]
	v_mfma_f32_16x16x32_bf16 v[108:111], v[128:131], v[198:201], v[108:111]
	v_mfma_f32_16x16x32_bf16 v[104:107], v[136:139], v[198:201], v[104:107]
	v_mfma_f32_16x16x32_bf16 v[92:95], v[128:131], v[206:209], v[92:95]
	v_mfma_f32_16x16x32_bf16 v[88:91], v[136:139], v[206:209], v[88:91]
	v_mfma_f32_16x16x32_bf16 v[76:79], v[128:131], v[214:217], v[76:79]
	v_mfma_f32_16x16x32_bf16 v[72:75], v[136:139], v[214:217], v[72:75]
	v_mfma_f32_16x16x32_bf16 v[124:127], v[132:135], v[194:197], v[124:127]
	v_mfma_f32_16x16x32_bf16 v[120:123], v[140:143], v[194:197], v[120:123]
	v_mfma_f32_16x16x32_bf16 v[108:111], v[132:135], v[202:205], v[108:111]
	v_mfma_f32_16x16x32_bf16 v[104:107], v[140:143], v[202:205], v[104:107]
	v_mfma_f32_16x16x32_bf16 v[92:95], v[132:135], v[210:213], v[92:95]
	v_mfma_f32_16x16x32_bf16 v[88:91], v[140:143], v[210:213], v[88:91]
	v_mfma_f32_16x16x32_bf16 v[76:79], v[132:135], v[236:239], v[76:79]
	v_mfma_f32_16x16x32_bf16 v[72:75], v[140:143], v[236:239], v[72:75]
	s_setprio 0
	s_setprio 1
	v_mfma_f32_16x16x32_bf16 v[116:119], v[156:159], v[190:193], v[116:119]
	v_mfma_f32_16x16x32_bf16 v[112:115], v[164:167], v[190:193], v[112:115]
	v_mfma_f32_16x16x32_bf16 v[100:103], v[156:159], v[198:201], v[100:103]
	v_mfma_f32_16x16x32_bf16 v[96:99], v[164:167], v[198:201], v[96:99]
	v_mfma_f32_16x16x32_bf16 v[84:87], v[156:159], v[206:209], v[84:87]
	v_mfma_f32_16x16x32_bf16 v[80:83], v[164:167], v[206:209], v[80:83]
	v_mfma_f32_16x16x32_bf16 v[68:71], v[156:159], v[214:217], v[68:71]
	v_mfma_f32_16x16x32_bf16 v[64:67], v[164:167], v[214:217], v[64:67]
	v_mfma_f32_16x16x32_bf16 v[116:119], v[160:163], v[194:197], v[116:119]
	v_mfma_f32_16x16x32_bf16 v[112:115], v[168:171], v[194:197], v[112:115]
	v_mfma_f32_16x16x32_bf16 v[100:103], v[160:163], v[202:205], v[100:103]
	v_mfma_f32_16x16x32_bf16 v[96:99], v[168:171], v[202:205], v[96:99]
	v_mfma_f32_16x16x32_bf16 v[84:87], v[160:163], v[210:213], v[84:87]
	v_mfma_f32_16x16x32_bf16 v[80:83], v[168:171], v[210:213], v[80:83]
	v_mfma_f32_16x16x32_bf16 v[68:71], v[160:163], v[236:239], v[68:71]
	v_mfma_f32_16x16x32_bf16 v[64:67], v[168:171], v[236:239], v[64:67]
	s_barrier
	s_setprio 0
	s_add_i32 s30, s52, s38
	v_lshl_add_u64 v[172:173], v[172:173], 0, s[0:1]
	s_mov_b32 m0, s30
	ds_read_b128 v[190:193], v189 offset:49152
	ds_read_b128 v[194:197], v189 offset:50176
	ds_read_b128 v[198:201], v189 offset:51200
	ds_read_b128 v[202:205], v189 offset:52224
	ds_read_b128 v[206:209], v189 offset:53248
	ds_read_b128 v[210:213], v189 offset:54272
	ds_read_b128 v[214:217], v189 offset:55296
	ds_read_b128 v[236:239], v189 offset:56320
	global_load_lds_dwordx4 v[172:173], off
	s_add_i32 m0, s30, 0x2000
	s_add_u32 s28, s28, 0x80080
	v_lshl_add_u64 v[172:173], v[218:219], 0, s[0:1]
	s_addc_u32 s29, s29, 0
	s_add_i32 s30, s53, s38
	global_load_lds_dwordx4 v[172:173], off
	v_lshl_add_u64 v[172:173], s[28:29], 0, v[146:147]
	s_mov_b32 m0, s30
	s_nop 0
	global_load_lds_dwordx4 v[172:173], off
	v_lshl_add_u64 v[172:173], s[28:29], 0, v[144:145]
	s_add_i32 m0, s30, 0x2000
	s_nop 0
	global_load_lds_dwordx4 v[172:173], off
	v_lshl_add_u64 v[172:173], v[228:229], 0, s[0:1]
	s_mov_b32 m0, s44
	s_nop 0
	global_load_lds_dwordx4 v[172:173], off
	v_lshl_add_u64 v[172:173], v[230:231], 0, s[0:1]
	s_mov_b32 m0, s45
	s_nop 0
	global_load_lds_dwordx4 v[172:173], off
	s_waitcnt vmcnt(8) lgkmcnt(0)
	s_setprio 1
	s_barrier
	v_mfma_f32_16x16x32_bf16 v[60:63], v[128:131], v[190:193], v[60:63]
	v_mfma_f32_16x16x32_bf16 v[56:59], v[136:139], v[190:193], v[56:59]
	v_mfma_f32_16x16x32_bf16 v[44:47], v[128:131], v[198:201], v[44:47]
	v_mfma_f32_16x16x32_bf16 v[40:43], v[136:139], v[198:201], v[40:43]
	v_mfma_f32_16x16x32_bf16 v[28:31], v[128:131], v[206:209], v[28:31]
	v_mfma_f32_16x16x32_bf16 v[24:27], v[136:139], v[206:209], v[24:27]
	v_mfma_f32_16x16x32_bf16 v[12:15], v[128:131], v[214:217], v[12:15]
	v_mfma_f32_16x16x32_bf16 v[8:11], v[136:139], v[214:217], v[8:11]
	v_mfma_f32_16x16x32_bf16 v[60:63], v[132:135], v[194:197], v[60:63]
	v_mfma_f32_16x16x32_bf16 v[56:59], v[140:143], v[194:197], v[56:59]
	v_mfma_f32_16x16x32_bf16 v[44:47], v[132:135], v[202:205], v[44:47]
	v_mfma_f32_16x16x32_bf16 v[40:43], v[140:143], v[202:205], v[40:43]
	v_mfma_f32_16x16x32_bf16 v[28:31], v[132:135], v[210:213], v[28:31]
	v_mfma_f32_16x16x32_bf16 v[24:27], v[140:143], v[210:213], v[24:27]
	v_mfma_f32_16x16x32_bf16 v[12:15], v[132:135], v[236:239], v[12:15]
	v_mfma_f32_16x16x32_bf16 v[8:11], v[140:143], v[236:239], v[8:11]
	s_setprio 0
	s_setprio 1
	v_mfma_f32_16x16x32_bf16 v[52:55], v[156:159], v[190:193], v[52:55]
	v_mfma_f32_16x16x32_bf16 v[48:51], v[164:167], v[190:193], v[48:51]
	v_mfma_f32_16x16x32_bf16 v[36:39], v[156:159], v[198:201], v[36:39]
	v_mfma_f32_16x16x32_bf16 v[32:35], v[164:167], v[198:201], v[32:35]
	v_mfma_f32_16x16x32_bf16 v[20:23], v[156:159], v[206:209], v[20:23]
	v_mfma_f32_16x16x32_bf16 v[16:19], v[164:167], v[206:209], v[16:19]
	v_mfma_f32_16x16x32_bf16 v[4:7], v[156:159], v[214:217], v[4:7]
	v_mfma_f32_16x16x32_bf16 v[0:3], v[164:167], v[214:217], v[0:3]
	v_mfma_f32_16x16x32_bf16 v[52:55], v[160:163], v[194:197], v[52:55]
	v_mfma_f32_16x16x32_bf16 v[48:51], v[168:171], v[194:197], v[48:51]
	v_mfma_f32_16x16x32_bf16 v[36:39], v[160:163], v[202:205], v[36:39]
	v_mfma_f32_16x16x32_bf16 v[32:35], v[168:171], v[202:205], v[32:35]
	v_mfma_f32_16x16x32_bf16 v[20:23], v[160:163], v[210:213], v[20:23]
	v_mfma_f32_16x16x32_bf16 v[16:19], v[168:171], v[210:213], v[16:19]
	v_mfma_f32_16x16x32_bf16 v[4:7], v[160:163], v[236:239], v[4:7]
	v_mfma_f32_16x16x32_bf16 v[0:3], v[168:171], v[236:239], v[0:3]
	s_barrier
	s_setprio 0
	s_add_i32 s51, s51, 2
	s_add_u32 s49, s49, 0x100
	s_addc_u32 s50, s50, 0
	s_add_u32 s6, s6, 0x100
	s_addc_u32 s7, s7, 0
	s_cmp_gt_u32 s51, 29
	s_cbranch_scc0 .LBB0_490
	s_and_b64 vcc, exec, s[12:13]
	s_cbranch_vccz .LBB0_493
	s_barrier
